# attention: next kv-head unit's Q and first K tiles requested during the current unit's last PV steps (two units unrolled)
# speedup vs baseline: 1.0562x; 1.0113x over previous
.Lau_entry:
	v_and_b32_e32 v3, 63, v0
	v_lshrrev_b32_e32 v4, 6, v0
	v_readfirstlane_b32 s75, v138
	v_and_b32_e32 v1, 15, v3
	v_readfirstlane_b32 s76, v4
	v_lshrrev_b32_e32 v2, 4, v3
	s_lshl_b32 s76, s76, 11
	s_add_i32 s76, s76, 0x24000
	v_lshl_add_u32 v4, v2, 2, v138
	ds_read2_b32 v[10:11], v4 offset0:0 offset1:4
	ds_read2_b32 v[12:13], v4 offset0:8 offset1:12
	ds_read2_b32 v[14:15], v4 offset0:16 offset1:20
	ds_read2_b32 v[16:17], v4 offset0:24 offset1:28
	ds_read2_b32 v[18:19], v4 offset0:32 offset1:36
	ds_read2_b32 v[20:21], v4 offset0:40 offset1:44
	ds_read2_b32 v[22:23], v4 offset0:48 offset1:52
	ds_read2_b32 v[24:25], v4 offset0:56 offset1:60
	ds_read2_b32 v[26:27], v4 offset0:64 offset1:68
	ds_read2_b32 v[28:29], v4 offset0:72 offset1:76
	ds_read2_b32 v[30:31], v4 offset0:80 offset1:84
	ds_read2_b32 v[32:33], v4 offset0:88 offset1:92
	ds_read2_b32 v[34:35], v4 offset0:96 offset1:100
	ds_read2_b32 v[36:37], v4 offset0:104 offset1:108
	ds_read2_b32 v[38:39], v4 offset0:112 offset1:116
	ds_read2_b32 v[40:41], v4 offset0:120 offset1:124
	ds_read2_b32 v[42:43], v4 offset0:128 offset1:132
	ds_read2_b32 v[44:45], v4 offset0:136 offset1:140
	ds_read2_b32 v[46:47], v4 offset0:144 offset1:148
	ds_read2_b32 v[48:49], v4 offset0:152 offset1:156
	ds_read2_b32 v[50:51], v4 offset0:160 offset1:164
	ds_read2_b32 v[52:53], v4 offset0:168 offset1:172
	ds_read2_b32 v[54:55], v4 offset0:176 offset1:180
	ds_read2_b32 v[56:57], v4 offset0:184 offset1:188
	ds_read2_b32 v[58:59], v4 offset0:192 offset1:196
	ds_read2_b32 v[60:61], v4 offset0:200 offset1:204
	ds_read2_b32 v[62:63], v4 offset0:208 offset1:212
	ds_read2_b32 v[64:65], v4 offset0:216 offset1:220
	ds_read2_b32 v[66:67], v4 offset0:224 offset1:228
	ds_read2_b32 v[68:69], v4 offset0:232 offset1:236
	ds_read2_b32 v[70:71], v4 offset0:240 offset1:244
	ds_read2_b32 v[72:73], v4 offset0:248 offset1:252
	v_readlane_b32 s40, v251, 27
	v_readlane_b32 s41, v251, 28
	v_readlane_b32 s42, v251, 29
	v_readlane_b32 s43, v251, 30
	v_readlane_b32 s44, v251, 31
	v_readlane_b32 s45, v251, 32
	v_readlane_b32 s46, v251, 49
	v_readlane_b32 s47, v251, 50
	s_lshl_b32 s8, s70, 11
	s_lshl_b32 s9, s72, 9
	s_add_u32 s56, s40, s8
	s_addc_u32 s57, s41, 0
	s_add_u32 s50, s42, s9
	s_addc_u32 s51, s43, 0
	s_add_u32 s52, s44, s9
	s_addc_u32 s53, s45, 0
	s_add_u32 s58, s46, s8
	s_addc_u32 s59, s47, 0
	v_lshlrev_b32_e32 v5, 1, v2
	v_xor_b32_e32 v5, v1, v5
	v_lshlrev_b32_e32 v5, 4, v5
	v_xor_b32_e32 v6, 0x80, v5
	v_and_b32_e32 v7, 3, v1
	v_and_b32_e32 v8, 8, v1
	v_lshl_or_b32 v8, v7, 1, v8
	v_or_b32_e32 v9, 0, v2
	v_xor_b32_e32 v9, v9, v8
	v_lshlrev_b32_e32 v9, 4, v9
	v_lshl_add_u32 v9, v1, 8, v9
	v_add_u32_e32 v74, s75, v9
	v_or_b32_e32 v9, 4, v2
	v_xor_b32_e32 v9, v9, v8
	v_lshlrev_b32_e32 v9, 4, v9
	v_lshl_add_u32 v9, v1, 8, v9
	v_add_u32_e32 v75, s75, v9
	v_or_b32_e32 v9, 8, v2
	v_xor_b32_e32 v9, v9, v8
	v_lshlrev_b32_e32 v9, 4, v9
	v_lshl_add_u32 v9, v1, 8, v9
	v_add_u32_e32 v76, s75, v9
	v_or_b32_e32 v9, 12, v2
	v_xor_b32_e32 v9, v9, v8
	v_lshlrev_b32_e32 v9, 4, v9
	v_lshl_add_u32 v9, v1, 8, v9
	v_add_u32_e32 v77, s75, v9
	v_lshrrev_b32_e32 v128, 2, v1
	v_lshl_or_b32 v129, v2, 3, v128
	v_and_b32_e32 v130, 1, v2
	v_lshl_or_b32 v130, v130, 2, v128
	v_lshlrev_b32_e32 v129, 8, v129
	v_lshl_add_u32 v129, v7, 3, v129
	v_add_u32_e32 v129, s75, v129
	v_xor_b32_e32 v9, 0, v130
	v_lshl_add_u32 v78, v9, 5, v129
	v_xor_b32_e32 v9, 1, v130
	v_lshl_add_u32 v79, v9, 5, v129
	v_xor_b32_e32 v9, 2, v130
	v_lshl_add_u32 v80, v9, 5, v129
	v_xor_b32_e32 v9, 3, v130
	v_lshl_add_u32 v81, v9, 5, v129
	v_xor_b32_e32 v9, 4, v130
	v_lshl_add_u32 v82, v9, 5, v129
	v_xor_b32_e32 v9, 5, v130
	v_lshl_add_u32 v83, v9, 5, v129
	v_xor_b32_e32 v9, 6, v130
	v_lshl_add_u32 v84, v9, 5, v129
	v_xor_b32_e32 v9, 7, v130
	v_lshl_add_u32 v85, v9, 5, v129
	v_lshl_add_u32 v86, v1, 4, s75
	v_lshl_add_u32 v87, v3, 4, s75
	v_lshl_add_u32 v88, v3, 1, s76
	v_cmp_gt_u32_e64 s[20:21], 4, v1
	v_lshlrev_b32_e32 v9, 4, v2
	v_lshl_add_u32 v128, v7, 9, v9
	v_add_u32_e32 v128, s76, v128
	v_add_u32_e32 v131, 0x22000, v9
	v_cndmask_b32_e64 v89, v131, v128, s[20:21]
	v_lshrrev_b32_e32 v128, 3, v1
	v_add_u32_e32 v128, v128, v1
	v_lshl_add_u32 v132, v128, 4, s75
	v_add_u32_e32 v132, 0x400, v132
	v_and_b32_e32 v128, 3, v3
	v_lshrrev_b32_e32 v129, 2, v3
	v_mul_u32_u24_e32 v131, 0x90, v129
	v_lshl_add_u32 v131, v128, 2, v131
	v_add_u32_e32 v133, s75, v131
	v_add_u32_e32 v133, 0x400, v133
	v_lshlrev_b32_e32 v129, 4, v129
	v_lshl_add_u32 v90, v128, 8, v129
	v_lshl_add_u32 v91, v7, 8, v9
	v_mov_b32_e32 v128, 0
	v_mov_b32_e32 v129, 0
	v_lshlrev_b32_e32 v9, 3, v3
	v_add_u32_e32 v9, 0x22000, v9
	ds_write_b64 v9, v[128:129]
	v_cmp_gt_u32_e64 s[24:25], s73, v3
	v_add_u32_e32 v9, 64, v3
	v_cmp_gt_u32_e64 s[26:27], s73, v9
	v_add_u32_e32 v9, 0x80, v3
	v_cmp_gt_u32_e64 s[28:29], s73, v9
	v_add_u32_e32 v9, 0xc0, v3
	v_cmp_gt_u32_e64 s[30:31], s73, v9
	s_waitcnt lgkmcnt(0)
	v_lshl_add_u32 v10, v10, 9, v5
	v_lshl_add_u32 v11, v11, 9, v5
	v_lshl_add_u32 v12, v12, 9, v6
	v_lshl_add_u32 v13, v13, 9, v6
	v_lshl_add_u32 v14, v14, 9, v5
	v_lshl_add_u32 v15, v15, 9, v5
	v_lshl_add_u32 v16, v16, 9, v6
	v_lshl_add_u32 v17, v17, 9, v6
	v_lshl_add_u32 v18, v18, 9, v5
	v_lshl_add_u32 v19, v19, 9, v5
	v_lshl_add_u32 v20, v20, 9, v6
	v_lshl_add_u32 v21, v21, 9, v6
	v_lshl_add_u32 v22, v22, 9, v5
	v_lshl_add_u32 v23, v23, 9, v5
	v_lshl_add_u32 v24, v24, 9, v6
	v_lshl_add_u32 v25, v25, 9, v6
	v_lshl_add_u32 v26, v26, 9, v5
	v_lshl_add_u32 v27, v27, 9, v5
	v_lshl_add_u32 v28, v28, 9, v6
	v_lshl_add_u32 v29, v29, 9, v6
	v_lshl_add_u32 v30, v30, 9, v5
	v_lshl_add_u32 v31, v31, 9, v5
	v_lshl_add_u32 v32, v32, 9, v6
	v_lshl_add_u32 v33, v33, 9, v6
	v_lshl_add_u32 v34, v34, 9, v5
	v_lshl_add_u32 v35, v35, 9, v5
	v_lshl_add_u32 v36, v36, 9, v6
	v_lshl_add_u32 v37, v37, 9, v6
	v_lshl_add_u32 v38, v38, 9, v5
	v_lshl_add_u32 v39, v39, 9, v5
	v_lshl_add_u32 v40, v40, 9, v6
	v_lshl_add_u32 v41, v41, 9, v6
	v_lshl_add_u32 v42, v42, 9, v5
	v_lshl_add_u32 v43, v43, 9, v5
	v_lshl_add_u32 v44, v44, 9, v6
	v_lshl_add_u32 v45, v45, 9, v6
	v_lshl_add_u32 v46, v46, 9, v5
	v_lshl_add_u32 v47, v47, 9, v5
	v_lshl_add_u32 v48, v48, 9, v6
	v_lshl_add_u32 v49, v49, 9, v6
	v_lshl_add_u32 v50, v50, 9, v5
	v_lshl_add_u32 v51, v51, 9, v5
	v_lshl_add_u32 v52, v52, 9, v6
	v_lshl_add_u32 v53, v53, 9, v6
	v_lshl_add_u32 v54, v54, 9, v5
	v_lshl_add_u32 v55, v55, 9, v5
	v_lshl_add_u32 v56, v56, 9, v6
	v_lshl_add_u32 v57, v57, 9, v6
	v_lshl_add_u32 v58, v58, 9, v5
	v_lshl_add_u32 v59, v59, 9, v5
	v_lshl_add_u32 v60, v60, 9, v6
	v_lshl_add_u32 v61, v61, 9, v6
	v_lshl_add_u32 v62, v62, 9, v5
	v_lshl_add_u32 v63, v63, 9, v5
	v_lshl_add_u32 v64, v64, 9, v6
	v_lshl_add_u32 v65, v65, 9, v6
	v_lshl_add_u32 v66, v66, 9, v5
	v_lshl_add_u32 v67, v67, 9, v5
	v_lshl_add_u32 v68, v68, 9, v6
	v_lshl_add_u32 v69, v69, 9, v6
	v_lshl_add_u32 v70, v70, 9, v5
	v_lshl_add_u32 v71, v71, 9, v5
	v_lshl_add_u32 v72, v72, 9, v6
	v_lshl_add_u32 v73, v73, 9, v6
	s_add_u32 s0, s50, 0
	s_addc_u32 s1, s51, 0
	s_add_u32 s2, s52, 0
	s_addc_u32 s3, s53, 0
	s_add_u32 s4, s56, 0
	s_addc_u32 s5, s57, 0
	s_add_u32 s6, s58, 0
	s_addc_u32 s7, s59, 0
	global_load_dwordx4 v[92:95], v91, s[4:5] offset:0
	global_load_dwordx4 v[96:99], v91, s[4:5] offset:64
	global_load_dwordx4 v[100:103], v91, s[4:5] offset:128
	global_load_dwordx4 v[104:107], v91, s[4:5] offset:192
	s_add_i32 m0, s75, 0x2400
	s_nop 0
	global_load_lds_dwordx4 v10, s[0:1]
	s_add_i32 m0, s75, 0x2800
	s_nop 0
	global_load_lds_dwordx4 v11, s[0:1]
	s_add_i32 m0, s75, 0x2c00
	s_nop 0
	global_load_lds_dwordx4 v12, s[0:1]
	s_add_i32 m0, s75, 0x3000
	s_nop 0
	global_load_lds_dwordx4 v13, s[0:1]
	s_add_i32 m0, s75, 0x3400
	s_nop 0
	global_load_lds_dwordx4 v14, s[0:1]
	s_add_i32 m0, s75, 0x3800
	s_nop 0
	global_load_lds_dwordx4 v15, s[0:1]
	s_add_i32 m0, s75, 0x3c00
	s_nop 0
	global_load_lds_dwordx4 v16, s[0:1]
	s_add_i32 m0, s75, 0x4000
	s_nop 0
	global_load_lds_dwordx4 v17, s[0:1]
	s_add_i32 m0, s75, 0x1400
	s_nop 0
	global_load_lds_dwordx4 v18, s[0:1]
	s_add_i32 m0, s75, 0x1800
	s_nop 0
	global_load_lds_dwordx4 v19, s[0:1]
	s_add_i32 m0, s75, 0x1c00
	s_nop 0
	global_load_lds_dwordx4 v20, s[0:1]
	s_add_i32 m0, s75, 0x2000
	s_nop 0
	global_load_lds_dwordx4 v21, s[0:1]
	s_waitcnt vmcnt(8)
	ds_read_b128 v[108:111], v74 offset:9216
	ds_read_b128 v[112:115], v75 offset:9216
	ds_read_b128 v[116:119], v76 offset:9216
	ds_read_b128 v[120:123], v77 offset:9216
	v_cndmask_b32_e64 v92, 0, v92, s[20:21]
	v_cndmask_b32_e64 v93, 0, v93, s[20:21]
	v_cndmask_b32_e64 v94, 0, v94, s[20:21]
	v_cndmask_b32_e64 v95, 0, v95, s[20:21]
	v_cndmask_b32_e64 v96, 0, v96, s[20:21]
	v_cndmask_b32_e64 v97, 0, v97, s[20:21]
	v_cndmask_b32_e64 v98, 0, v98, s[20:21]
	v_cndmask_b32_e64 v99, 0, v99, s[20:21]
	v_cndmask_b32_e64 v100, 0, v100, s[20:21]
	v_cndmask_b32_e64 v101, 0, v101, s[20:21]
	v_cndmask_b32_e64 v102, 0, v102, s[20:21]
	v_cndmask_b32_e64 v103, 0, v103, s[20:21]
	v_cndmask_b32_e64 v104, 0, v104, s[20:21]
	v_cndmask_b32_e64 v105, 0, v105, s[20:21]
	v_cndmask_b32_e64 v106, 0, v106, s[20:21]
	v_cndmask_b32_e64 v107, 0, v107, s[20:21]
	s_waitcnt lgkmcnt(0)
	v_mfma_f32_16x16x32_bf16 v[124:127], v[92:95], v[108:111], 0
	s_add_i32 m0, s75, 0x2400
	v_mfma_f32_16x16x32_bf16 v[124:127], v[96:99], v[112:115], v[124:127]
	global_load_lds_dwordx4 v22, s[0:1]
	s_add_i32 m0, s75, 0x2800
	v_mfma_f32_16x16x32_bf16 v[124:127], v[100:103], v[116:119], v[124:127]
	global_load_lds_dwordx4 v23, s[0:1]
	s_add_i32 m0, s75, 0x2c00
	v_mfma_f32_16x16x32_bf16 v[124:127], v[104:107], v[120:123], v[124:127]
	global_load_lds_dwordx4 v24, s[0:1]
	s_add_i32 m0, s75, 0x3000
	s_nop 0
	global_load_lds_dwordx4 v25, s[0:1]
	s_nop 5
	s_mov_b64 exec, 0xffff
	ds_write_b128 v86, v[124:127] offset:1024
	s_mov_b64 exec, -1
	s_waitcnt vmcnt(8)
	ds_read_b128 v[108:111], v74 offset:13312
	ds_read_b128 v[112:115], v75 offset:13312
	ds_read_b128 v[116:119], v76 offset:13312
	ds_read_b128 v[120:123], v77 offset:13312
	s_waitcnt lgkmcnt(0)
	v_mfma_f32_16x16x32_bf16 v[124:127], v[92:95], v[108:111], 0
	s_add_i32 m0, s75, 0x3400
	v_mfma_f32_16x16x32_bf16 v[124:127], v[96:99], v[112:115], v[124:127]
	global_load_lds_dwordx4 v26, s[0:1]
	s_add_i32 m0, s75, 0x3800
	v_mfma_f32_16x16x32_bf16 v[124:127], v[100:103], v[116:119], v[124:127]
	global_load_lds_dwordx4 v27, s[0:1]
	s_add_i32 m0, s75, 0x3c00
	v_mfma_f32_16x16x32_bf16 v[124:127], v[104:107], v[120:123], v[124:127]
	global_load_lds_dwordx4 v28, s[0:1]
	s_add_i32 m0, s75, 0x4000
	s_nop 0
	global_load_lds_dwordx4 v29, s[0:1]
	s_nop 5
	s_mov_b64 exec, 0xffff
	ds_write_b128 v86, v[124:127] offset:1280
	s_mov_b64 exec, -1
	s_waitcnt vmcnt(8)
	ds_read_b128 v[108:111], v74 offset:5120
	ds_read_b128 v[112:115], v75 offset:5120
	ds_read_b128 v[116:119], v76 offset:5120
	ds_read_b128 v[120:123], v77 offset:5120
	s_waitcnt lgkmcnt(0)
	v_mfma_f32_16x16x32_bf16 v[124:127], v[92:95], v[108:111], 0
	s_add_i32 m0, s75, 0x1400
	v_mfma_f32_16x16x32_bf16 v[124:127], v[96:99], v[112:115], v[124:127]
	global_load_lds_dwordx4 v30, s[0:1]
	s_add_i32 m0, s75, 0x1800
	v_mfma_f32_16x16x32_bf16 v[124:127], v[100:103], v[116:119], v[124:127]
	global_load_lds_dwordx4 v31, s[0:1]
	s_add_i32 m0, s75, 0x1c00
	v_mfma_f32_16x16x32_bf16 v[124:127], v[104:107], v[120:123], v[124:127]
	global_load_lds_dwordx4 v32, s[0:1]
	s_add_i32 m0, s75, 0x2000
	s_nop 0
	global_load_lds_dwordx4 v33, s[0:1]
	s_nop 5
	s_mov_b64 exec, 0xffff
	ds_write_b128 v86, v[124:127] offset:1536
	s_mov_b64 exec, -1
	s_waitcnt vmcnt(8)
	ds_read_b128 v[108:111], v74 offset:9216
	ds_read_b128 v[112:115], v75 offset:9216
	ds_read_b128 v[116:119], v76 offset:9216
	ds_read_b128 v[120:123], v77 offset:9216
	s_waitcnt lgkmcnt(0)
	v_mfma_f32_16x16x32_bf16 v[124:127], v[92:95], v[108:111], 0
	s_add_i32 m0, s75, 0x2400
	v_mfma_f32_16x16x32_bf16 v[124:127], v[96:99], v[112:115], v[124:127]
	global_load_lds_dwordx4 v34, s[0:1]
	s_add_i32 m0, s75, 0x2800
	v_mfma_f32_16x16x32_bf16 v[124:127], v[100:103], v[116:119], v[124:127]
	global_load_lds_dwordx4 v35, s[0:1]
	s_add_i32 m0, s75, 0x2c00
	v_mfma_f32_16x16x32_bf16 v[124:127], v[104:107], v[120:123], v[124:127]
	global_load_lds_dwordx4 v36, s[0:1]
	s_add_i32 m0, s75, 0x3000
	s_nop 0
	global_load_lds_dwordx4 v37, s[0:1]
	s_nop 5
	s_mov_b64 exec, 0xffff
	ds_write_b128 v86, v[124:127] offset:1792
	s_mov_b64 exec, -1
	s_waitcnt vmcnt(8)
	ds_read_b128 v[108:111], v74 offset:13312
	ds_read_b128 v[112:115], v75 offset:13312
	ds_read_b128 v[116:119], v76 offset:13312
	ds_read_b128 v[120:123], v77 offset:13312
	s_waitcnt lgkmcnt(0)
	v_mfma_f32_16x16x32_bf16 v[124:127], v[92:95], v[108:111], 0
	s_add_i32 m0, s75, 0x3400
	v_mfma_f32_16x16x32_bf16 v[124:127], v[96:99], v[112:115], v[124:127]
	global_load_lds_dwordx4 v38, s[0:1]
	s_add_i32 m0, s75, 0x3800
	v_mfma_f32_16x16x32_bf16 v[124:127], v[100:103], v[116:119], v[124:127]
	global_load_lds_dwordx4 v39, s[0:1]
	s_add_i32 m0, s75, 0x3c00
	v_mfma_f32_16x16x32_bf16 v[124:127], v[104:107], v[120:123], v[124:127]
	global_load_lds_dwordx4 v40, s[0:1]
	s_add_i32 m0, s75, 0x4000
	s_nop 0
	global_load_lds_dwordx4 v41, s[0:1]
	s_nop 5
	s_mov_b64 exec, 0xffff
	ds_write_b128 v86, v[124:127] offset:2048
	s_mov_b64 exec, -1
	s_waitcnt vmcnt(8)
	ds_read_b128 v[108:111], v74 offset:5120
	ds_read_b128 v[112:115], v75 offset:5120
	ds_read_b128 v[116:119], v76 offset:5120
	ds_read_b128 v[120:123], v77 offset:5120
	s_waitcnt lgkmcnt(0)
	v_mfma_f32_16x16x32_bf16 v[124:127], v[92:95], v[108:111], 0
	s_add_i32 m0, s75, 0x1400
	v_mfma_f32_16x16x32_bf16 v[124:127], v[96:99], v[112:115], v[124:127]
	global_load_lds_dwordx4 v42, s[0:1]
	s_add_i32 m0, s75, 0x1800
	v_mfma_f32_16x16x32_bf16 v[124:127], v[100:103], v[116:119], v[124:127]
	global_load_lds_dwordx4 v43, s[0:1]
	s_add_i32 m0, s75, 0x1c00
	v_mfma_f32_16x16x32_bf16 v[124:127], v[104:107], v[120:123], v[124:127]
	global_load_lds_dwordx4 v44, s[0:1]
	s_add_i32 m0, s75, 0x2000
	s_nop 0
	global_load_lds_dwordx4 v45, s[0:1]
	s_nop 5
	s_mov_b64 exec, 0xffff
	ds_write_b128 v86, v[124:127] offset:2304
	s_mov_b64 exec, -1
	s_waitcnt vmcnt(8)
	ds_read_b128 v[108:111], v74 offset:9216
	ds_read_b128 v[112:115], v75 offset:9216
	ds_read_b128 v[116:119], v76 offset:9216
	ds_read_b128 v[120:123], v77 offset:9216
	s_waitcnt lgkmcnt(0)
	v_mfma_f32_16x16x32_bf16 v[124:127], v[92:95], v[108:111], 0
	s_add_i32 m0, s75, 0x2400
	v_mfma_f32_16x16x32_bf16 v[124:127], v[96:99], v[112:115], v[124:127]
	global_load_lds_dwordx4 v46, s[0:1]
	s_add_i32 m0, s75, 0x2800
	v_mfma_f32_16x16x32_bf16 v[124:127], v[100:103], v[116:119], v[124:127]
	global_load_lds_dwordx4 v47, s[0:1]
	s_add_i32 m0, s75, 0x2c00
	v_mfma_f32_16x16x32_bf16 v[124:127], v[104:107], v[120:123], v[124:127]
	global_load_lds_dwordx4 v48, s[0:1]
	s_add_i32 m0, s75, 0x3000
	s_nop 0
	global_load_lds_dwordx4 v49, s[0:1]
	s_nop 5
	s_mov_b64 exec, 0xffff
	ds_write_b128 v86, v[124:127] offset:2560
	s_mov_b64 exec, -1
	s_waitcnt vmcnt(8)
	ds_read_b128 v[108:111], v74 offset:13312
	ds_read_b128 v[112:115], v75 offset:13312
	ds_read_b128 v[116:119], v76 offset:13312
	ds_read_b128 v[120:123], v77 offset:13312
	s_waitcnt lgkmcnt(0)
	v_mfma_f32_16x16x32_bf16 v[124:127], v[92:95], v[108:111], 0
	s_add_i32 m0, s75, 0x3400
	v_mfma_f32_16x16x32_bf16 v[124:127], v[96:99], v[112:115], v[124:127]
	global_load_lds_dwordx4 v50, s[0:1]
	s_add_i32 m0, s75, 0x3800
	v_mfma_f32_16x16x32_bf16 v[124:127], v[100:103], v[116:119], v[124:127]
	global_load_lds_dwordx4 v51, s[0:1]
	s_add_i32 m0, s75, 0x3c00
	v_mfma_f32_16x16x32_bf16 v[124:127], v[104:107], v[120:123], v[124:127]
	global_load_lds_dwordx4 v52, s[0:1]
	s_add_i32 m0, s75, 0x4000
	s_nop 0
	global_load_lds_dwordx4 v53, s[0:1]
	s_nop 5
	s_mov_b64 exec, 0xffff
	ds_write_b128 v86, v[124:127] offset:2816
	s_mov_b64 exec, -1
	s_waitcnt vmcnt(8)
	ds_read_b128 v[108:111], v74 offset:5120
	ds_read_b128 v[112:115], v75 offset:5120
	ds_read_b128 v[116:119], v76 offset:5120
	ds_read_b128 v[120:123], v77 offset:5120
	s_waitcnt lgkmcnt(0)
	v_mfma_f32_16x16x32_bf16 v[124:127], v[92:95], v[108:111], 0
	s_add_i32 m0, s75, 0x1400
	v_mfma_f32_16x16x32_bf16 v[124:127], v[96:99], v[112:115], v[124:127]
	global_load_lds_dwordx4 v54, s[0:1]
	s_add_i32 m0, s75, 0x1800
	v_mfma_f32_16x16x32_bf16 v[124:127], v[100:103], v[116:119], v[124:127]
	global_load_lds_dwordx4 v55, s[0:1]
	s_add_i32 m0, s75, 0x1c00
	v_mfma_f32_16x16x32_bf16 v[124:127], v[104:107], v[120:123], v[124:127]
	global_load_lds_dwordx4 v56, s[0:1]
	s_add_i32 m0, s75, 0x2000
	s_nop 0
	global_load_lds_dwordx4 v57, s[0:1]
	s_nop 5
	s_mov_b64 exec, 0xffff
	ds_write_b128 v86, v[124:127] offset:3072
	s_mov_b64 exec, -1
	s_waitcnt vmcnt(8)
	ds_read_b128 v[108:111], v74 offset:9216
	ds_read_b128 v[112:115], v75 offset:9216
	ds_read_b128 v[116:119], v76 offset:9216
	ds_read_b128 v[120:123], v77 offset:9216
	s_waitcnt lgkmcnt(0)
	v_mfma_f32_16x16x32_bf16 v[124:127], v[92:95], v[108:111], 0
	s_add_i32 m0, s75, 0x2400
	v_mfma_f32_16x16x32_bf16 v[124:127], v[96:99], v[112:115], v[124:127]
	global_load_lds_dwordx4 v58, s[0:1]
	s_add_i32 m0, s75, 0x2800
	v_mfma_f32_16x16x32_bf16 v[124:127], v[100:103], v[116:119], v[124:127]
	global_load_lds_dwordx4 v59, s[0:1]
	s_add_i32 m0, s75, 0x2c00
	v_mfma_f32_16x16x32_bf16 v[124:127], v[104:107], v[120:123], v[124:127]
	global_load_lds_dwordx4 v60, s[0:1]
	s_add_i32 m0, s75, 0x3000
	s_nop 0
	global_load_lds_dwordx4 v61, s[0:1]
	s_nop 5
	s_mov_b64 exec, 0xffff
	ds_write_b128 v86, v[124:127] offset:3328
	s_mov_b64 exec, -1
	s_waitcnt vmcnt(8)
	ds_read_b128 v[108:111], v74 offset:13312
	ds_read_b128 v[112:115], v75 offset:13312
	ds_read_b128 v[116:119], v76 offset:13312
	ds_read_b128 v[120:123], v77 offset:13312
	s_waitcnt lgkmcnt(0)
	v_mfma_f32_16x16x32_bf16 v[124:127], v[92:95], v[108:111], 0
	s_add_i32 m0, s75, 0x3400
	v_mfma_f32_16x16x32_bf16 v[124:127], v[96:99], v[112:115], v[124:127]
	global_load_lds_dwordx4 v62, s[0:1]
	s_add_i32 m0, s75, 0x3800
	v_mfma_f32_16x16x32_bf16 v[124:127], v[100:103], v[116:119], v[124:127]
	global_load_lds_dwordx4 v63, s[0:1]
	s_add_i32 m0, s75, 0x3c00
	v_mfma_f32_16x16x32_bf16 v[124:127], v[104:107], v[120:123], v[124:127]
	global_load_lds_dwordx4 v64, s[0:1]
	s_add_i32 m0, s75, 0x4000
	s_nop 0
	global_load_lds_dwordx4 v65, s[0:1]
	s_nop 5
	s_mov_b64 exec, 0xffff
	ds_write_b128 v86, v[124:127] offset:3584
	s_mov_b64 exec, -1
	s_waitcnt vmcnt(8)
	ds_read_b128 v[108:111], v74 offset:5120
	ds_read_b128 v[112:115], v75 offset:5120
	ds_read_b128 v[116:119], v76 offset:5120
	ds_read_b128 v[120:123], v77 offset:5120
	s_waitcnt lgkmcnt(0)
	v_mfma_f32_16x16x32_bf16 v[124:127], v[92:95], v[108:111], 0
	s_add_i32 m0, s75, 0x1400
	v_mfma_f32_16x16x32_bf16 v[124:127], v[96:99], v[112:115], v[124:127]
	global_load_lds_dwordx4 v66, s[0:1]
	s_add_i32 m0, s75, 0x1800
	v_mfma_f32_16x16x32_bf16 v[124:127], v[100:103], v[116:119], v[124:127]
	global_load_lds_dwordx4 v67, s[0:1]
	s_add_i32 m0, s75, 0x1c00
	v_mfma_f32_16x16x32_bf16 v[124:127], v[104:107], v[120:123], v[124:127]
	global_load_lds_dwordx4 v68, s[0:1]
	s_add_i32 m0, s75, 0x2000
	s_nop 0
	global_load_lds_dwordx4 v69, s[0:1]
	s_nop 5
	s_mov_b64 exec, 0xffff
	ds_write_b128 v86, v[124:127] offset:3840
	s_mov_b64 exec, -1
	s_waitcnt vmcnt(8)
	ds_read_b128 v[108:111], v74 offset:9216
	ds_read_b128 v[112:115], v75 offset:9216
	ds_read_b128 v[116:119], v76 offset:9216
	ds_read_b128 v[120:123], v77 offset:9216
	s_waitcnt lgkmcnt(0)
	v_mfma_f32_16x16x32_bf16 v[124:127], v[92:95], v[108:111], 0
	s_add_i32 m0, s75, 0x2400
	v_mfma_f32_16x16x32_bf16 v[124:127], v[96:99], v[112:115], v[124:127]
	global_load_lds_dwordx4 v70, s[0:1]
	s_add_i32 m0, s75, 0x2800
	v_mfma_f32_16x16x32_bf16 v[124:127], v[100:103], v[116:119], v[124:127]
	global_load_lds_dwordx4 v71, s[0:1]
	s_add_i32 m0, s75, 0x2c00
	v_mfma_f32_16x16x32_bf16 v[124:127], v[104:107], v[120:123], v[124:127]
	global_load_lds_dwordx4 v72, s[0:1]
	s_add_i32 m0, s75, 0x3000
	s_nop 0
	global_load_lds_dwordx4 v73, s[0:1]
	s_nop 5
	s_mov_b64 exec, 0xffff
	ds_write_b128 v86, v[124:127] offset:4096
	s_mov_b64 exec, -1
	s_waitcnt vmcnt(8)
	ds_read_b128 v[108:111], v74 offset:13312
	ds_read_b128 v[112:115], v75 offset:13312
	ds_read_b128 v[116:119], v76 offset:13312
	ds_read_b128 v[120:123], v77 offset:13312
	s_waitcnt lgkmcnt(0)
	v_mfma_f32_16x16x32_bf16 v[124:127], v[92:95], v[108:111], 0
	v_mfma_f32_16x16x32_bf16 v[124:127], v[96:99], v[112:115], v[124:127]
	v_mfma_f32_16x16x32_bf16 v[124:127], v[100:103], v[116:119], v[124:127]
	v_mfma_f32_16x16x32_bf16 v[124:127], v[104:107], v[120:123], v[124:127]
	s_nop 7
	s_nop 0
	s_mov_b64 exec, 0xffff
	ds_write_b128 v86, v[124:127] offset:4352
	s_mov_b64 exec, -1
	s_waitcnt vmcnt(4)
	ds_read_b128 v[108:111], v74 offset:5120
	ds_read_b128 v[112:115], v75 offset:5120
	ds_read_b128 v[116:119], v76 offset:5120
	ds_read_b128 v[120:123], v77 offset:5120
	s_waitcnt lgkmcnt(0)
	v_mfma_f32_16x16x32_bf16 v[124:127], v[92:95], v[108:111], 0
	v_mfma_f32_16x16x32_bf16 v[124:127], v[96:99], v[112:115], v[124:127]
	v_mfma_f32_16x16x32_bf16 v[124:127], v[100:103], v[116:119], v[124:127]
	v_mfma_f32_16x16x32_bf16 v[124:127], v[104:107], v[120:123], v[124:127]
	s_nop 7
	s_nop 0
	s_mov_b64 exec, 0xffff
	ds_write_b128 v86, v[124:127] offset:4608
	s_mov_b64 exec, -1
	s_waitcnt vmcnt(0)
	ds_read_b128 v[108:111], v74 offset:9216
	ds_read_b128 v[112:115], v75 offset:9216
	ds_read_b128 v[116:119], v76 offset:9216
	ds_read_b128 v[120:123], v77 offset:9216
	s_waitcnt lgkmcnt(0)
	v_mfma_f32_16x16x32_bf16 v[124:127], v[92:95], v[108:111], 0
	v_mfma_f32_16x16x32_bf16 v[124:127], v[96:99], v[112:115], v[124:127]
	v_mfma_f32_16x16x32_bf16 v[124:127], v[100:103], v[116:119], v[124:127]
	v_mfma_f32_16x16x32_bf16 v[124:127], v[104:107], v[120:123], v[124:127]
	s_nop 7
	s_nop 0
	s_mov_b64 exec, 0xffff
	ds_write_b128 v86, v[124:127] offset:4864
	s_mov_b64 exec, -1
	s_add_i32 m0, s75, 0x2400
	s_nop 0
	global_load_lds_dwordx4 v10, s[2:3]
	s_add_i32 m0, s75, 0x2800
	s_nop 0
	global_load_lds_dwordx4 v11, s[2:3]
	s_add_i32 m0, s75, 0x2c00
	s_nop 0
	global_load_lds_dwordx4 v12, s[2:3]
	s_add_i32 m0, s75, 0x3000
	s_nop 0
	global_load_lds_dwordx4 v13, s[2:3]
	s_add_i32 m0, s75, 0x3400
	s_nop 0
	global_load_lds_dwordx4 v14, s[2:3]
	s_add_i32 m0, s75, 0x3800
	s_nop 0
	global_load_lds_dwordx4 v15, s[2:3]
	s_add_i32 m0, s75, 0x3c00
	s_nop 0
	global_load_lds_dwordx4 v16, s[2:3]
	s_add_i32 m0, s75, 0x4000
	s_nop 0
	global_load_lds_dwordx4 v17, s[2:3]
	s_waitcnt lgkmcnt(0)
	ds_read_b128 v[108:111], v87 offset:1024
	ds_read_b128 v[112:115], v87 offset:2048
	ds_read_b128 v[116:119], v87 offset:3072
	ds_read_b128 v[120:123], v87 offset:4096
	s_waitcnt lgkmcnt(0)
	s_add_i32 m0, s75, 0x400
	s_nop 0
	global_load_lds_dwordx4 v18, s[2:3]
	s_add_i32 m0, s75, 0x800
	s_nop 0
	global_load_lds_dwordx4 v19, s[2:3]
	s_add_i32 m0, s75, 0xc00
	s_nop 0
	global_load_lds_dwordx4 v20, s[2:3]
	s_add_i32 m0, s75, 0x1000
	s_nop 0
	global_load_lds_dwordx4 v21, s[2:3]
	s_add_i32 m0, s75, 0x1400
	s_nop 0
	global_load_lds_dwordx4 v22, s[2:3]
	s_add_i32 m0, s75, 0x1800
	s_nop 0
	global_load_lds_dwordx4 v23, s[2:3]
	s_add_i32 m0, s75, 0x1c00
	s_nop 0
	global_load_lds_dwordx4 v24, s[2:3]
	s_add_i32 m0, s75, 0x2000
	s_nop 0
	global_load_lds_dwordx4 v25, s[2:3]
	s_cmp_eq_u32 s73, 0x100
	s_cbranch_scc1 .Lau_nomask1_0
	v_mov_b32_e32 v9, 0xff61b1e6
	v_cndmask_b32_e64 v108, v9, v108, s[24:25]
	v_cndmask_b32_e64 v109, v9, v109, s[24:25]
	v_cndmask_b32_e64 v110, v9, v110, s[24:25]
	v_cndmask_b32_e64 v111, v9, v111, s[24:25]
	v_cndmask_b32_e64 v112, v9, v112, s[26:27]
	v_cndmask_b32_e64 v113, v9, v113, s[26:27]
	v_cndmask_b32_e64 v114, v9, v114, s[26:27]
	v_cndmask_b32_e64 v115, v9, v115, s[26:27]
	v_cndmask_b32_e64 v116, v9, v116, s[28:29]
	v_cndmask_b32_e64 v117, v9, v117, s[28:29]
	v_cndmask_b32_e64 v118, v9, v118, s[28:29]
	v_cndmask_b32_e64 v119, v9, v119, s[28:29]
	v_cndmask_b32_e64 v120, v9, v120, s[30:31]
	v_cndmask_b32_e64 v121, v9, v121, s[30:31]
	v_cndmask_b32_e64 v122, v9, v122, s[30:31]
	v_cndmask_b32_e64 v123, v9, v123, s[30:31]

.Lau_nomask2_0:
	s_nop 0
	v_add_f32_e32 v216, 0, v108
	v_add_f32_e32 v217, 0, v109
	v_add_f32_e32 v218, 0, v110
	v_add_f32_e32 v219, 0, v111
	v_add_f32_e32 v216, v112, v216
	v_add_f32_e32 v217, v113, v217
	v_add_f32_e32 v218, v114, v218
	v_add_f32_e32 v219, v115, v219
	v_add_f32_e32 v216, v116, v216
	v_add_f32_e32 v217, v117, v217
	v_add_f32_e32 v218, v118, v218
	v_add_f32_e32 v219, v119, v219
	v_add_f32_e32 v216, v120, v216
	v_add_f32_e32 v217, v121, v217
	v_add_f32_e32 v218, v122, v218
	v_add_f32_e32 v219, v123, v219
	v_add_f32_dpp v216, v216, v216 quad_perm:[1,0,3,2] row_mask:0xf bank_mask:0xf bound_ctrl:1
	v_add_f32_dpp v217, v217, v217 quad_perm:[1,0,3,2] row_mask:0xf bank_mask:0xf bound_ctrl:1
	v_add_f32_dpp v218, v218, v218 quad_perm:[1,0,3,2] row_mask:0xf bank_mask:0xf bound_ctrl:1
	v_add_f32_dpp v219, v219, v219 quad_perm:[1,0,3,2] row_mask:0xf bank_mask:0xf bound_ctrl:1
	v_add_f32_dpp v216, v216, v216 quad_perm:[2,3,0,1] row_mask:0xf bank_mask:0xf bound_ctrl:1
	v_add_f32_dpp v217, v217, v217 quad_perm:[2,3,0,1] row_mask:0xf bank_mask:0xf bound_ctrl:1
	v_add_f32_dpp v218, v218, v218 quad_perm:[2,3,0,1] row_mask:0xf bank_mask:0xf bound_ctrl:1
	v_add_f32_dpp v219, v219, v219 quad_perm:[2,3,0,1] row_mask:0xf bank_mask:0xf bound_ctrl:1
	v_add_f32_dpp v216, v216, v216 row_half_mirror row_mask:0xf bank_mask:0xf bound_ctrl:1
	v_add_f32_dpp v217, v217, v217 row_half_mirror row_mask:0xf bank_mask:0xf bound_ctrl:1
	v_add_f32_dpp v218, v218, v218 row_half_mirror row_mask:0xf bank_mask:0xf bound_ctrl:1
	v_add_f32_dpp v219, v219, v219 row_half_mirror row_mask:0xf bank_mask:0xf bound_ctrl:1
	v_add_f32_dpp v216, v216, v216 row_mirror row_mask:0xf bank_mask:0xf bound_ctrl:1
	v_add_f32_dpp v217, v217, v217 row_mirror row_mask:0xf bank_mask:0xf bound_ctrl:1
	v_add_f32_dpp v218, v218, v218 row_mirror row_mask:0xf bank_mask:0xf bound_ctrl:1
	v_add_f32_dpp v219, v219, v219 row_mirror row_mask:0xf bank_mask:0xf bound_ctrl:1
	v_add_f32_dpp v216, v216, v216 row_bcast:15 row_mask:0xa bank_mask:0xf
	v_add_f32_dpp v217, v217, v217 row_bcast:15 row_mask:0xa bank_mask:0xf
	v_add_f32_dpp v218, v218, v218 row_bcast:15 row_mask:0xa bank_mask:0xf
	v_add_f32_dpp v219, v219, v219 row_bcast:15 row_mask:0xa bank_mask:0xf
	v_add_f32_dpp v216, v216, v216 row_bcast:31 row_mask:0xc bank_mask:0xf
	v_add_f32_dpp v217, v217, v217 row_bcast:31 row_mask:0xc bank_mask:0xf
	v_add_f32_dpp v218, v218, v218 row_bcast:31 row_mask:0xc bank_mask:0xf
	v_add_f32_dpp v219, v219, v219 row_bcast:31 row_mask:0xc bank_mask:0xf
	s_nop 0
	v_readlane_b32 s84, v216, 63
	v_readlane_b32 s85, v217, 63
	v_readlane_b32 s86, v218, 63
	v_readlane_b32 s87, v219, 63
	s_nop 1
	v_mov_b32_e32 v216, s84
	v_mov_b32_e32 v217, s85
	v_mov_b32_e32 v218, s86
	v_mov_b32_e32 v219, s87
	v_div_scale_f32 v220, s[8:9], v216, v216, 1.0
	v_div_scale_f32 v221, s[8:9], v217, v217, 1.0
	v_div_scale_f32 v222, s[8:9], v218, v218, 1.0
	v_div_scale_f32 v223, s[8:9], v219, v219, 1.0
	v_rcp_f32_e32 v128, v220
	v_rcp_f32_e32 v129, v221
	v_rcp_f32_e32 v130, v222
	v_rcp_f32_e32 v131, v223
	s_nop 0
	v_fma_f32 v124, -v220, v128, 1.0
	v_fma_f32 v125, -v221, v129, 1.0
	v_fma_f32 v126, -v222, v130, 1.0
	v_fma_f32 v127, -v223, v131, 1.0
	v_fmac_f32_e32 v128, v124, v128
	v_fmac_f32_e32 v129, v125, v129
	v_fmac_f32_e32 v130, v126, v130
	v_fmac_f32_e32 v131, v127, v131
	v_div_scale_f32 v224, vcc, 1.0, v216, 1.0
	v_mul_f32_e32 v225, v224, v128
	v_fma_f32 v134, -v220, v225, v224
	v_fmac_f32_e32 v225, v134, v128
	v_fma_f32 v220, -v220, v225, v224
	s_nop 0
	v_div_fmas_f32 v220, v220, v128, v225
	v_div_fixup_f32 v220, v220, v216, 1.0
	v_div_scale_f32 v224, vcc, 1.0, v217, 1.0
	v_mul_f32_e32 v225, v224, v129
	v_fma_f32 v134, -v221, v225, v224
	v_fmac_f32_e32 v225, v134, v129
	v_fma_f32 v221, -v221, v225, v224
	s_nop 0
	v_div_fmas_f32 v221, v221, v129, v225
	v_div_fixup_f32 v221, v221, v217, 1.0
	v_div_scale_f32 v224, vcc, 1.0, v218, 1.0
	v_mul_f32_e32 v225, v224, v130
	v_fma_f32 v134, -v222, v225, v224
	v_fmac_f32_e32 v225, v134, v130
	v_fma_f32 v222, -v222, v225, v224
	s_nop 0
	v_div_fmas_f32 v222, v222, v130, v225
	v_div_fixup_f32 v222, v222, v218, 1.0
	v_div_scale_f32 v224, vcc, 1.0, v219, 1.0
	v_mul_f32_e32 v225, v224, v131
	v_fma_f32 v134, -v223, v225, v224
	v_fmac_f32_e32 v225, v134, v131
	v_fma_f32 v223, -v223, v225, v224
	s_nop 0
	v_div_fmas_f32 v223, v223, v131, v225
	v_div_fixup_f32 v223, v223, v219, 1.0
	v_mul_f32_e32 v108, v108, v220
	v_mul_f32_e32 v109, v109, v221
	v_mul_f32_e32 v110, v110, v222
	v_mul_f32_e32 v111, v111, v223
	v_mul_f32_e32 v112, v112, v220
	v_mul_f32_e32 v113, v113, v221
	v_mul_f32_e32 v114, v114, v222
	v_mul_f32_e32 v115, v115, v223
	v_mul_f32_e32 v116, v116, v220
	v_mul_f32_e32 v117, v117, v221
	v_mul_f32_e32 v118, v118, v222
	v_mul_f32_e32 v119, v119, v223
	v_mul_f32_e32 v120, v120, v220
	v_mul_f32_e32 v121, v121, v221
	v_mul_f32_e32 v122, v122, v222
	v_mul_f32_e32 v123, v123, v223
	v_cvt_pk_bf16_f32 v108, v108, v108
	v_cvt_pk_bf16_f32 v109, v109, v109
	v_cvt_pk_bf16_f32 v110, v110, v110
	v_cvt_pk_bf16_f32 v111, v111, v111
	v_cvt_pk_bf16_f32 v112, v112, v112
	v_cvt_pk_bf16_f32 v113, v113, v113
	v_cvt_pk_bf16_f32 v114, v114, v114
	v_cvt_pk_bf16_f32 v115, v115, v115
	v_cvt_pk_bf16_f32 v116, v116, v116
	v_cvt_pk_bf16_f32 v117, v117, v117
	v_cvt_pk_bf16_f32 v118, v118, v118
	v_cvt_pk_bf16_f32 v119, v119, v119
	v_cvt_pk_bf16_f32 v120, v120, v120
	v_cvt_pk_bf16_f32 v121, v121, v121
	v_cvt_pk_bf16_f32 v122, v122, v122
	v_cvt_pk_bf16_f32 v123, v123, v123
	ds_write_b16 v88, v108 offset:0
	ds_write_b16 v88, v109 offset:512
	ds_write_b16 v88, v110 offset:1024
	ds_write_b16 v88, v111 offset:1536
	ds_write_b16 v88, v112 offset:128
	ds_write_b16 v88, v113 offset:640
	ds_write_b16 v88, v114 offset:1152
	ds_write_b16 v88, v115 offset:1664
	ds_write_b16 v88, v116 offset:256
	ds_write_b16 v88, v117 offset:768
	ds_write_b16 v88, v118 offset:1280
	ds_write_b16 v88, v119 offset:1792
	ds_write_b16 v88, v120 offset:384
	ds_write_b16 v88, v121 offset:896
	ds_write_b16 v88, v122 offset:1408
	ds_write_b16 v88, v123 offset:1920
	s_waitcnt vmcnt(8)
	s_waitcnt lgkmcnt(0)
	ds_read_b128 v[172:175], v89 offset:0
	ds_read_b64_tr_b16 v[140:141], v78 offset:9216
	ds_read_b64_tr_b16 v[142:143], v78 offset:10240
	ds_read_b64_tr_b16 v[144:145], v79 offset:9216
	ds_read_b64_tr_b16 v[146:147], v79 offset:10240
	ds_read_b64_tr_b16 v[148:149], v80 offset:9216
	ds_read_b64_tr_b16 v[150:151], v80 offset:10240
	ds_read_b64_tr_b16 v[152:153], v81 offset:9216
	ds_read_b64_tr_b16 v[154:155], v81 offset:10240
	ds_read_b64_tr_b16 v[156:157], v82 offset:9216
	ds_read_b64_tr_b16 v[158:159], v82 offset:10240
	ds_read_b64_tr_b16 v[160:161], v83 offset:9216
	ds_read_b64_tr_b16 v[162:163], v83 offset:10240
	ds_read_b64_tr_b16 v[164:165], v84 offset:9216
	ds_read_b64_tr_b16 v[166:167], v84 offset:10240
	ds_read_b64_tr_b16 v[168:169], v85 offset:9216
	ds_read_b64_tr_b16 v[170:171], v85 offset:10240
	s_waitcnt lgkmcnt(0)
	v_mfma_f32_16x16x32_bf16 v[184:187], v[172:175], v[140:143], 0
	s_add_i32 m0, s75, 0x2400
	v_mfma_f32_16x16x32_bf16 v[188:191], v[172:175], v[144:147], 0
	global_load_lds_dwordx4 v26, s[2:3]
	s_add_i32 m0, s75, 0x2800
	v_mfma_f32_16x16x32_bf16 v[192:195], v[172:175], v[148:151], 0
	global_load_lds_dwordx4 v27, s[2:3]
	s_add_i32 m0, s75, 0x2c00
	v_mfma_f32_16x16x32_bf16 v[196:199], v[172:175], v[152:155], 0
	global_load_lds_dwordx4 v28, s[2:3]
	s_add_i32 m0, s75, 0x3000
	v_mfma_f32_16x16x32_bf16 v[200:203], v[172:175], v[156:159], 0
	global_load_lds_dwordx4 v29, s[2:3]
	s_add_i32 m0, s75, 0x3400
	v_mfma_f32_16x16x32_bf16 v[204:207], v[172:175], v[160:163], 0
	global_load_lds_dwordx4 v30, s[2:3]
	s_add_i32 m0, s75, 0x3800
	v_mfma_f32_16x16x32_bf16 v[208:211], v[172:175], v[164:167], 0
	global_load_lds_dwordx4 v31, s[2:3]
	s_add_i32 m0, s75, 0x3c00
	v_mfma_f32_16x16x32_bf16 v[212:215], v[172:175], v[168:171], 0
	global_load_lds_dwordx4 v32, s[2:3]
	s_add_i32 m0, s75, 0x4000
	s_nop 0
	global_load_lds_dwordx4 v33, s[2:3]
	s_waitcnt vmcnt(8)
	ds_read_b128 v[172:175], v89 offset:64
	ds_read_b64_tr_b16 v[140:141], v78 offset:1024
	ds_read_b64_tr_b16 v[142:143], v78 offset:2048
	ds_read_b64_tr_b16 v[144:145], v79 offset:1024
	ds_read_b64_tr_b16 v[146:147], v79 offset:2048
	ds_read_b64_tr_b16 v[148:149], v80 offset:1024
	ds_read_b64_tr_b16 v[150:151], v80 offset:2048
	ds_read_b64_tr_b16 v[152:153], v81 offset:1024
	ds_read_b64_tr_b16 v[154:155], v81 offset:2048
	ds_read_b64_tr_b16 v[156:157], v82 offset:1024
	ds_read_b64_tr_b16 v[158:159], v82 offset:2048
	ds_read_b64_tr_b16 v[160:161], v83 offset:1024
	ds_read_b64_tr_b16 v[162:163], v83 offset:2048
	ds_read_b64_tr_b16 v[164:165], v84 offset:1024
	ds_read_b64_tr_b16 v[166:167], v84 offset:2048
	ds_read_b64_tr_b16 v[168:169], v85 offset:1024
	ds_read_b64_tr_b16 v[170:171], v85 offset:2048
	s_waitcnt lgkmcnt(0)
	v_mfma_f32_16x16x32_bf16 v[184:187], v[172:175], v[140:143], v[184:187]
	s_add_i32 m0, s75, 0x400
	v_mfma_f32_16x16x32_bf16 v[188:191], v[172:175], v[144:147], v[188:191]
	global_load_lds_dwordx4 v34, s[2:3]
	s_add_i32 m0, s75, 0x800
	v_mfma_f32_16x16x32_bf16 v[192:195], v[172:175], v[148:151], v[192:195]
	global_load_lds_dwordx4 v35, s[2:3]
	s_add_i32 m0, s75, 0xc00
	v_mfma_f32_16x16x32_bf16 v[196:199], v[172:175], v[152:155], v[196:199]
	global_load_lds_dwordx4 v36, s[2:3]
	s_add_i32 m0, s75, 0x1000
	v_mfma_f32_16x16x32_bf16 v[200:203], v[172:175], v[156:159], v[200:203]
	global_load_lds_dwordx4 v37, s[2:3]
	s_add_i32 m0, s75, 0x1400
	v_mfma_f32_16x16x32_bf16 v[204:207], v[172:175], v[160:163], v[204:207]
	global_load_lds_dwordx4 v38, s[2:3]
	s_add_i32 m0, s75, 0x1800
	v_mfma_f32_16x16x32_bf16 v[208:211], v[172:175], v[164:167], v[208:211]
	global_load_lds_dwordx4 v39, s[2:3]
	s_add_i32 m0, s75, 0x1c00
	v_mfma_f32_16x16x32_bf16 v[212:215], v[172:175], v[168:171], v[212:215]
	global_load_lds_dwordx4 v40, s[2:3]
	s_add_i32 m0, s75, 0x2000
	s_nop 0
	global_load_lds_dwordx4 v41, s[2:3]
	s_waitcnt vmcnt(8)
	ds_read_b128 v[172:175], v89 offset:128
	ds_read_b64_tr_b16 v[140:141], v78 offset:9216
	ds_read_b64_tr_b16 v[142:143], v78 offset:10240
	ds_read_b64_tr_b16 v[144:145], v79 offset:9216
	ds_read_b64_tr_b16 v[146:147], v79 offset:10240
	ds_read_b64_tr_b16 v[148:149], v80 offset:9216
	ds_read_b64_tr_b16 v[150:151], v80 offset:10240
	ds_read_b64_tr_b16 v[152:153], v81 offset:9216
	ds_read_b64_tr_b16 v[154:155], v81 offset:10240
	ds_read_b64_tr_b16 v[156:157], v82 offset:9216
	ds_read_b64_tr_b16 v[158:159], v82 offset:10240
	ds_read_b64_tr_b16 v[160:161], v83 offset:9216
	ds_read_b64_tr_b16 v[162:163], v83 offset:10240
	ds_read_b64_tr_b16 v[164:165], v84 offset:9216
	ds_read_b64_tr_b16 v[166:167], v84 offset:10240
	ds_read_b64_tr_b16 v[168:169], v85 offset:9216
	ds_read_b64_tr_b16 v[170:171], v85 offset:10240
	s_waitcnt lgkmcnt(0)
	v_mfma_f32_16x16x32_bf16 v[184:187], v[172:175], v[140:143], v[184:187]
	s_add_i32 m0, s75, 0x2400
	v_mfma_f32_16x16x32_bf16 v[188:191], v[172:175], v[144:147], v[188:191]
	global_load_lds_dwordx4 v42, s[2:3]
	s_add_i32 m0, s75, 0x2800
	v_mfma_f32_16x16x32_bf16 v[192:195], v[172:175], v[148:151], v[192:195]
	global_load_lds_dwordx4 v43, s[2:3]
	s_add_i32 m0, s75, 0x2c00
	v_mfma_f32_16x16x32_bf16 v[196:199], v[172:175], v[152:155], v[196:199]
	global_load_lds_dwordx4 v44, s[2:3]
	s_add_i32 m0, s75, 0x3000
	v_mfma_f32_16x16x32_bf16 v[200:203], v[172:175], v[156:159], v[200:203]
	global_load_lds_dwordx4 v45, s[2:3]
	s_add_i32 m0, s75, 0x3400
	v_mfma_f32_16x16x32_bf16 v[204:207], v[172:175], v[160:163], v[204:207]
	global_load_lds_dwordx4 v46, s[2:3]
	s_add_i32 m0, s75, 0x3800
	v_mfma_f32_16x16x32_bf16 v[208:211], v[172:175], v[164:167], v[208:211]
	global_load_lds_dwordx4 v47, s[2:3]
	s_add_i32 m0, s75, 0x3c00
	v_mfma_f32_16x16x32_bf16 v[212:215], v[172:175], v[168:171], v[212:215]
	global_load_lds_dwordx4 v48, s[2:3]
	s_add_i32 m0, s75, 0x4000
	s_nop 0
	global_load_lds_dwordx4 v49, s[2:3]
	s_waitcnt vmcnt(8)
	ds_read_b128 v[172:175], v89 offset:192
	ds_read_b64_tr_b16 v[140:141], v78 offset:1024
	ds_read_b64_tr_b16 v[142:143], v78 offset:2048
	ds_read_b64_tr_b16 v[144:145], v79 offset:1024
	ds_read_b64_tr_b16 v[146:147], v79 offset:2048
	ds_read_b64_tr_b16 v[148:149], v80 offset:1024
	ds_read_b64_tr_b16 v[150:151], v80 offset:2048
	ds_read_b64_tr_b16 v[152:153], v81 offset:1024
	ds_read_b64_tr_b16 v[154:155], v81 offset:2048
	ds_read_b64_tr_b16 v[156:157], v82 offset:1024
	ds_read_b64_tr_b16 v[158:159], v82 offset:2048
	ds_read_b64_tr_b16 v[160:161], v83 offset:1024
	ds_read_b64_tr_b16 v[162:163], v83 offset:2048
	ds_read_b64_tr_b16 v[164:165], v84 offset:1024
	ds_read_b64_tr_b16 v[166:167], v84 offset:2048
	ds_read_b64_tr_b16 v[168:169], v85 offset:1024
	ds_read_b64_tr_b16 v[170:171], v85 offset:2048
	s_waitcnt lgkmcnt(0)
	v_mfma_f32_16x16x32_bf16 v[184:187], v[172:175], v[140:143], v[184:187]
	s_add_i32 m0, s75, 0x400
	v_mfma_f32_16x16x32_bf16 v[188:191], v[172:175], v[144:147], v[188:191]
	global_load_lds_dwordx4 v50, s[2:3]
	s_add_i32 m0, s75, 0x800
	v_mfma_f32_16x16x32_bf16 v[192:195], v[172:175], v[148:151], v[192:195]
	global_load_lds_dwordx4 v51, s[2:3]
	s_add_i32 m0, s75, 0xc00
	v_mfma_f32_16x16x32_bf16 v[196:199], v[172:175], v[152:155], v[196:199]
	global_load_lds_dwordx4 v52, s[2:3]
	s_add_i32 m0, s75, 0x1000
	v_mfma_f32_16x16x32_bf16 v[200:203], v[172:175], v[156:159], v[200:203]
	global_load_lds_dwordx4 v53, s[2:3]
	s_add_i32 m0, s75, 0x1400
	v_mfma_f32_16x16x32_bf16 v[204:207], v[172:175], v[160:163], v[204:207]
	global_load_lds_dwordx4 v54, s[2:3]
	s_add_i32 m0, s75, 0x1800
	v_mfma_f32_16x16x32_bf16 v[208:211], v[172:175], v[164:167], v[208:211]
	global_load_lds_dwordx4 v55, s[2:3]
	s_add_i32 m0, s75, 0x1c00
	v_mfma_f32_16x16x32_bf16 v[212:215], v[172:175], v[168:171], v[212:215]
	global_load_lds_dwordx4 v56, s[2:3]
	s_add_i32 m0, s75, 0x2000
	s_nop 0
	global_load_lds_dwordx4 v57, s[2:3]
	s_waitcnt vmcnt(8)
	ds_read_b128 v[172:175], v89 offset:256
	ds_read_b64_tr_b16 v[140:141], v78 offset:9216
	ds_read_b64_tr_b16 v[142:143], v78 offset:10240
	ds_read_b64_tr_b16 v[144:145], v79 offset:9216
	ds_read_b64_tr_b16 v[146:147], v79 offset:10240
	ds_read_b64_tr_b16 v[148:149], v80 offset:9216
	ds_read_b64_tr_b16 v[150:151], v80 offset:10240
	ds_read_b64_tr_b16 v[152:153], v81 offset:9216
	ds_read_b64_tr_b16 v[154:155], v81 offset:10240
	ds_read_b64_tr_b16 v[156:157], v82 offset:9216
	ds_read_b64_tr_b16 v[158:159], v82 offset:10240
	ds_read_b64_tr_b16 v[160:161], v83 offset:9216
	ds_read_b64_tr_b16 v[162:163], v83 offset:10240
	ds_read_b64_tr_b16 v[164:165], v84 offset:9216
	ds_read_b64_tr_b16 v[166:167], v84 offset:10240
	ds_read_b64_tr_b16 v[168:169], v85 offset:9216
	ds_read_b64_tr_b16 v[170:171], v85 offset:10240
	s_waitcnt lgkmcnt(0)
	v_mfma_f32_16x16x32_bf16 v[184:187], v[172:175], v[140:143], v[184:187]
	s_add_i32 m0, s75, 0x2400
	v_mfma_f32_16x16x32_bf16 v[188:191], v[172:175], v[144:147], v[188:191]
	global_load_lds_dwordx4 v58, s[2:3]
	s_add_i32 m0, s75, 0x2800
	v_mfma_f32_16x16x32_bf16 v[192:195], v[172:175], v[148:151], v[192:195]
	global_load_lds_dwordx4 v59, s[2:3]
	s_add_i32 m0, s75, 0x2c00
	v_mfma_f32_16x16x32_bf16 v[196:199], v[172:175], v[152:155], v[196:199]
	global_load_lds_dwordx4 v60, s[2:3]
	s_add_i32 m0, s75, 0x3000
	v_mfma_f32_16x16x32_bf16 v[200:203], v[172:175], v[156:159], v[200:203]
	global_load_lds_dwordx4 v61, s[2:3]
	s_add_i32 m0, s75, 0x3400
	v_mfma_f32_16x16x32_bf16 v[204:207], v[172:175], v[160:163], v[204:207]
	global_load_lds_dwordx4 v62, s[2:3]
	s_add_i32 m0, s75, 0x3800
	v_mfma_f32_16x16x32_bf16 v[208:211], v[172:175], v[164:167], v[208:211]
	global_load_lds_dwordx4 v63, s[2:3]
	s_add_i32 m0, s75, 0x3c00
	v_mfma_f32_16x16x32_bf16 v[212:215], v[172:175], v[168:171], v[212:215]
	global_load_lds_dwordx4 v64, s[2:3]
	s_add_i32 m0, s75, 0x4000
	s_nop 0
	global_load_lds_dwordx4 v65, s[2:3]
	s_waitcnt vmcnt(8)
	ds_read_b128 v[172:175], v89 offset:320
	ds_read_b64_tr_b16 v[140:141], v78 offset:1024
	ds_read_b64_tr_b16 v[142:143], v78 offset:2048
	ds_read_b64_tr_b16 v[144:145], v79 offset:1024
	ds_read_b64_tr_b16 v[146:147], v79 offset:2048
	ds_read_b64_tr_b16 v[148:149], v80 offset:1024
	ds_read_b64_tr_b16 v[150:151], v80 offset:2048
	ds_read_b64_tr_b16 v[152:153], v81 offset:1024
	ds_read_b64_tr_b16 v[154:155], v81 offset:2048
	ds_read_b64_tr_b16 v[156:157], v82 offset:1024
	ds_read_b64_tr_b16 v[158:159], v82 offset:2048
	ds_read_b64_tr_b16 v[160:161], v83 offset:1024
	ds_read_b64_tr_b16 v[162:163], v83 offset:2048
	ds_read_b64_tr_b16 v[164:165], v84 offset:1024
	ds_read_b64_tr_b16 v[166:167], v84 offset:2048
	ds_read_b64_tr_b16 v[168:169], v85 offset:1024
	ds_read_b64_tr_b16 v[170:171], v85 offset:2048
	s_waitcnt lgkmcnt(0)
	v_mfma_f32_16x16x32_bf16 v[184:187], v[172:175], v[140:143], v[184:187]
	s_add_i32 m0, s75, 0x400
	v_mfma_f32_16x16x32_bf16 v[188:191], v[172:175], v[144:147], v[188:191]
	global_load_lds_dwordx4 v66, s[2:3]
	s_add_i32 m0, s75, 0x800
	v_mfma_f32_16x16x32_bf16 v[192:195], v[172:175], v[148:151], v[192:195]
	global_load_lds_dwordx4 v67, s[2:3]
	s_add_i32 m0, s75, 0xc00
	v_mfma_f32_16x16x32_bf16 v[196:199], v[172:175], v[152:155], v[196:199]
	global_load_lds_dwordx4 v68, s[2:3]
	s_add_i32 m0, s75, 0x1000
	v_mfma_f32_16x16x32_bf16 v[200:203], v[172:175], v[156:159], v[200:203]
	global_load_lds_dwordx4 v69, s[2:3]
	s_add_i32 m0, s75, 0x1400
	v_mfma_f32_16x16x32_bf16 v[204:207], v[172:175], v[160:163], v[204:207]
	global_load_lds_dwordx4 v70, s[2:3]
	s_add_i32 m0, s75, 0x1800
	v_mfma_f32_16x16x32_bf16 v[208:211], v[172:175], v[164:167], v[208:211]
	global_load_lds_dwordx4 v71, s[2:3]
	s_add_i32 m0, s75, 0x1c00
	v_mfma_f32_16x16x32_bf16 v[212:215], v[172:175], v[168:171], v[212:215]
	global_load_lds_dwordx4 v72, s[2:3]
	s_add_i32 m0, s75, 0x2000
	s_nop 0
	global_load_lds_dwordx4 v73, s[2:3]
	s_waitcnt vmcnt(8)
	ds_read_b128 v[172:175], v89 offset:384
	ds_read_b64_tr_b16 v[140:141], v78 offset:9216
	ds_read_b64_tr_b16 v[142:143], v78 offset:10240
	ds_read_b64_tr_b16 v[144:145], v79 offset:9216
	ds_read_b64_tr_b16 v[146:147], v79 offset:10240
	ds_read_b64_tr_b16 v[148:149], v80 offset:9216
	ds_read_b64_tr_b16 v[150:151], v80 offset:10240
	ds_read_b64_tr_b16 v[152:153], v81 offset:9216
	ds_read_b64_tr_b16 v[154:155], v81 offset:10240
	ds_read_b64_tr_b16 v[156:157], v82 offset:9216
	ds_read_b64_tr_b16 v[158:159], v82 offset:10240
	ds_read_b64_tr_b16 v[160:161], v83 offset:9216
	ds_read_b64_tr_b16 v[162:163], v83 offset:10240
	ds_read_b64_tr_b16 v[164:165], v84 offset:9216
	ds_read_b64_tr_b16 v[166:167], v84 offset:10240
	ds_read_b64_tr_b16 v[168:169], v85 offset:9216
	ds_read_b64_tr_b16 v[170:171], v85 offset:10240
	s_waitcnt lgkmcnt(0)
	s_add_u32 s0, s0, 0x100
	s_addc_u32 s1, s1, 0
	s_add_u32 s4, s4, 0x400
	s_addc_u32 s5, s5, 0
	global_load_dwordx4 v[92:95], v91, s[4:5] offset:0
	global_load_dwordx4 v[96:99], v91, s[4:5] offset:64
	global_load_dwordx4 v[100:103], v91, s[4:5] offset:128
	global_load_dwordx4 v[104:107], v91, s[4:5] offset:192
	v_mfma_f32_16x16x32_bf16 v[184:187], v[172:175], v[140:143], v[184:187]
	s_add_i32 m0, s75, 0x2400
	v_mfma_f32_16x16x32_bf16 v[188:191], v[172:175], v[144:147], v[188:191]
	global_load_lds_dwordx4 v10, s[0:1]
	s_add_i32 m0, s75, 0x2800
	v_mfma_f32_16x16x32_bf16 v[192:195], v[172:175], v[148:151], v[192:195]
	global_load_lds_dwordx4 v11, s[0:1]
	s_add_i32 m0, s75, 0x2c00
	v_mfma_f32_16x16x32_bf16 v[196:199], v[172:175], v[152:155], v[196:199]
	global_load_lds_dwordx4 v12, s[0:1]
	s_add_i32 m0, s75, 0x3000
	v_mfma_f32_16x16x32_bf16 v[200:203], v[172:175], v[156:159], v[200:203]
	global_load_lds_dwordx4 v13, s[0:1]
	s_add_i32 m0, s75, 0x3400
	v_mfma_f32_16x16x32_bf16 v[204:207], v[172:175], v[160:163], v[204:207]
	global_load_lds_dwordx4 v14, s[0:1]
	s_add_i32 m0, s75, 0x3800
	v_mfma_f32_16x16x32_bf16 v[208:211], v[172:175], v[164:167], v[208:211]
	global_load_lds_dwordx4 v15, s[0:1]
	s_add_i32 m0, s75, 0x3c00
	v_mfma_f32_16x16x32_bf16 v[212:215], v[172:175], v[168:171], v[212:215]
	global_load_lds_dwordx4 v16, s[0:1]
	s_add_i32 m0, s75, 0x4000
	s_nop 0
	global_load_lds_dwordx4 v17, s[0:1]
	s_waitcnt vmcnt(12)
	ds_read_b128 v[172:175], v89 offset:448
	ds_read_b64_tr_b16 v[140:141], v78 offset:1024
	ds_read_b64_tr_b16 v[142:143], v78 offset:2048
	ds_read_b64_tr_b16 v[144:145], v79 offset:1024
	ds_read_b64_tr_b16 v[146:147], v79 offset:2048
	ds_read_b64_tr_b16 v[148:149], v80 offset:1024
	ds_read_b64_tr_b16 v[150:151], v80 offset:2048
	ds_read_b64_tr_b16 v[152:153], v81 offset:1024
	ds_read_b64_tr_b16 v[154:155], v81 offset:2048
	ds_read_b64_tr_b16 v[156:157], v82 offset:1024
	ds_read_b64_tr_b16 v[158:159], v82 offset:2048
	ds_read_b64_tr_b16 v[160:161], v83 offset:1024
	ds_read_b64_tr_b16 v[162:163], v83 offset:2048
	ds_read_b64_tr_b16 v[164:165], v84 offset:1024
	ds_read_b64_tr_b16 v[166:167], v84 offset:2048
	ds_read_b64_tr_b16 v[168:169], v85 offset:1024
	ds_read_b64_tr_b16 v[170:171], v85 offset:2048
	s_waitcnt lgkmcnt(0)
	v_mfma_f32_16x16x32_bf16 v[184:187], v[172:175], v[140:143], v[184:187]
	s_add_i32 m0, s75, 0x1400
	v_mfma_f32_16x16x32_bf16 v[188:191], v[172:175], v[144:147], v[188:191]
	global_load_lds_dwordx4 v18, s[0:1]
	s_add_i32 m0, s75, 0x1800
	v_mfma_f32_16x16x32_bf16 v[192:195], v[172:175], v[148:151], v[192:195]
	global_load_lds_dwordx4 v19, s[0:1]
	s_add_i32 m0, s75, 0x1c00
	v_mfma_f32_16x16x32_bf16 v[196:199], v[172:175], v[152:155], v[196:199]
	global_load_lds_dwordx4 v20, s[0:1]
	s_add_i32 m0, s75, 0x2000
	v_mfma_f32_16x16x32_bf16 v[200:203], v[172:175], v[156:159], v[200:203]
	global_load_lds_dwordx4 v21, s[0:1]
	v_mfma_f32_16x16x32_bf16 v[204:207], v[172:175], v[160:163], v[204:207]
	v_mfma_f32_16x16x32_bf16 v[208:211], v[172:175], v[164:167], v[208:211]
	v_mfma_f32_16x16x32_bf16 v[212:215], v[172:175], v[168:171], v[212:215]
	s_nop 7
	s_mov_b64 exec, 0xffff
	ds_write_b128 v132, v[184:187] offset:0
	ds_write_b128 v132, v[188:191] offset:288
	ds_write_b128 v132, v[192:195] offset:576
	ds_write_b128 v132, v[196:199] offset:864
	ds_write_b128 v132, v[200:203] offset:1152
	ds_write_b128 v132, v[204:207] offset:1440
	ds_write_b128 v132, v[208:211] offset:1728
	ds_write_b128 v132, v[212:215] offset:2016
	s_mov_b64 exec, -1
	s_waitcnt lgkmcnt(0)
	ds_read_b32 v140, v133 offset:0
	ds_read_b32 v141, v133 offset:16
	ds_read_b32 v142, v133 offset:32
	ds_read_b32 v143, v133 offset:48
	ds_read_b32 v144, v133 offset:64
	ds_read_b32 v145, v133 offset:80
	ds_read_b32 v146, v133 offset:96
	ds_read_b32 v147, v133 offset:112
	s_waitcnt lgkmcnt(0)
	v_cvt_pk_bf16_f32 v148, v140, v141
	v_cvt_pk_bf16_f32 v149, v142, v143
	v_cvt_pk_bf16_f32 v150, v144, v145
	v_cvt_pk_bf16_f32 v151, v146, v147
	global_store_dwordx4 v90, v[148:151], s[6:7]
	s_add_u32 s2, s52, 0x100
	s_addc_u32 s3, s53, 0
	s_add_u32 s6, s58, 0x400
	s_addc_u32 s7, s59, 0
	s_waitcnt vmcnt(4)
	ds_read_b128 v[108:111], v74 offset:9216
	ds_read_b128 v[112:115], v75 offset:9216
	ds_read_b128 v[116:119], v76 offset:9216
	ds_read_b128 v[120:123], v77 offset:9216
	v_cndmask_b32_e64 v92, 0, v92, s[20:21]
	v_cndmask_b32_e64 v93, 0, v93, s[20:21]
	v_cndmask_b32_e64 v94, 0, v94, s[20:21]
	v_cndmask_b32_e64 v95, 0, v95, s[20:21]
	v_cndmask_b32_e64 v96, 0, v96, s[20:21]
	v_cndmask_b32_e64 v97, 0, v97, s[20:21]
	v_cndmask_b32_e64 v98, 0, v98, s[20:21]
	v_cndmask_b32_e64 v99, 0, v99, s[20:21]
	v_cndmask_b32_e64 v100, 0, v100, s[20:21]
	v_cndmask_b32_e64 v101, 0, v101, s[20:21]
	v_cndmask_b32_e64 v102, 0, v102, s[20:21]
	v_cndmask_b32_e64 v103, 0, v103, s[20:21]
	v_cndmask_b32_e64 v104, 0, v104, s[20:21]
	v_cndmask_b32_e64 v105, 0, v105, s[20:21]
	v_cndmask_b32_e64 v106, 0, v106, s[20:21]
	v_cndmask_b32_e64 v107, 0, v107, s[20:21]
	s_waitcnt lgkmcnt(0)
	v_mfma_f32_16x16x32_bf16 v[124:127], v[92:95], v[108:111], 0
	s_add_i32 m0, s75, 0x2400
	v_mfma_f32_16x16x32_bf16 v[124:127], v[96:99], v[112:115], v[124:127]
	global_load_lds_dwordx4 v22, s[0:1]
	s_add_i32 m0, s75, 0x2800
	v_mfma_f32_16x16x32_bf16 v[124:127], v[100:103], v[116:119], v[124:127]
	global_load_lds_dwordx4 v23, s[0:1]
	s_add_i32 m0, s75, 0x2c00
	v_mfma_f32_16x16x32_bf16 v[124:127], v[104:107], v[120:123], v[124:127]
	global_load_lds_dwordx4 v24, s[0:1]
	s_add_i32 m0, s75, 0x3000
	s_nop 0
	global_load_lds_dwordx4 v25, s[0:1]
	s_nop 5
	s_mov_b64 exec, 0xffff
	ds_write_b128 v86, v[124:127] offset:1024
	s_mov_b64 exec, -1
	s_waitcnt vmcnt(8)
	ds_read_b128 v[108:111], v74 offset:13312
	ds_read_b128 v[112:115], v75 offset:13312
	ds_read_b128 v[116:119], v76 offset:13312
	ds_read_b128 v[120:123], v77 offset:13312
	s_waitcnt lgkmcnt(0)
	v_mfma_f32_16x16x32_bf16 v[124:127], v[92:95], v[108:111], 0
	s_add_i32 m0, s75, 0x3400
	v_mfma_f32_16x16x32_bf16 v[124:127], v[96:99], v[112:115], v[124:127]
	global_load_lds_dwordx4 v26, s[0:1]
	s_add_i32 m0, s75, 0x3800
	v_mfma_f32_16x16x32_bf16 v[124:127], v[100:103], v[116:119], v[124:127]
	global_load_lds_dwordx4 v27, s[0:1]
	s_add_i32 m0, s75, 0x3c00
	v_mfma_f32_16x16x32_bf16 v[124:127], v[104:107], v[120:123], v[124:127]
	global_load_lds_dwordx4 v28, s[0:1]
	s_add_i32 m0, s75, 0x4000
	s_nop 0
	global_load_lds_dwordx4 v29, s[0:1]
	s_nop 5
	s_mov_b64 exec, 0xffff
	ds_write_b128 v86, v[124:127] offset:1280
	s_mov_b64 exec, -1
	s_waitcnt vmcnt(8)
	ds_read_b128 v[108:111], v74 offset:5120
	ds_read_b128 v[112:115], v75 offset:5120
	ds_read_b128 v[116:119], v76 offset:5120
	ds_read_b128 v[120:123], v77 offset:5120
	s_waitcnt lgkmcnt(0)
	v_mfma_f32_16x16x32_bf16 v[124:127], v[92:95], v[108:111], 0
	s_add_i32 m0, s75, 0x1400
	v_mfma_f32_16x16x32_bf16 v[124:127], v[96:99], v[112:115], v[124:127]
	global_load_lds_dwordx4 v30, s[0:1]
	s_add_i32 m0, s75, 0x1800
	v_mfma_f32_16x16x32_bf16 v[124:127], v[100:103], v[116:119], v[124:127]
	global_load_lds_dwordx4 v31, s[0:1]
	s_add_i32 m0, s75, 0x1c00
	v_mfma_f32_16x16x32_bf16 v[124:127], v[104:107], v[120:123], v[124:127]
	global_load_lds_dwordx4 v32, s[0:1]
	s_add_i32 m0, s75, 0x2000
	s_nop 0
	global_load_lds_dwordx4 v33, s[0:1]
	s_nop 5
	s_mov_b64 exec, 0xffff
	ds_write_b128 v86, v[124:127] offset:1536
	s_mov_b64 exec, -1
	s_waitcnt vmcnt(8)
	ds_read_b128 v[108:111], v74 offset:9216
	ds_read_b128 v[112:115], v75 offset:9216
	ds_read_b128 v[116:119], v76 offset:9216
	ds_read_b128 v[120:123], v77 offset:9216
	s_waitcnt lgkmcnt(0)
	v_mfma_f32_16x16x32_bf16 v[124:127], v[92:95], v[108:111], 0
	s_add_i32 m0, s75, 0x2400
	v_mfma_f32_16x16x32_bf16 v[124:127], v[96:99], v[112:115], v[124:127]
	global_load_lds_dwordx4 v34, s[0:1]
	s_add_i32 m0, s75, 0x2800
	v_mfma_f32_16x16x32_bf16 v[124:127], v[100:103], v[116:119], v[124:127]
	global_load_lds_dwordx4 v35, s[0:1]
	s_add_i32 m0, s75, 0x2c00
	v_mfma_f32_16x16x32_bf16 v[124:127], v[104:107], v[120:123], v[124:127]
	global_load_lds_dwordx4 v36, s[0:1]
	s_add_i32 m0, s75, 0x3000
	s_nop 0
	global_load_lds_dwordx4 v37, s[0:1]
	s_nop 5
	s_mov_b64 exec, 0xffff
	ds_write_b128 v86, v[124:127] offset:1792
	s_mov_b64 exec, -1
	s_waitcnt vmcnt(8)
	ds_read_b128 v[108:111], v74 offset:13312
	ds_read_b128 v[112:115], v75 offset:13312
	ds_read_b128 v[116:119], v76 offset:13312
	ds_read_b128 v[120:123], v77 offset:13312
	s_waitcnt lgkmcnt(0)
	v_mfma_f32_16x16x32_bf16 v[124:127], v[92:95], v[108:111], 0
	s_add_i32 m0, s75, 0x3400
	v_mfma_f32_16x16x32_bf16 v[124:127], v[96:99], v[112:115], v[124:127]
	global_load_lds_dwordx4 v38, s[0:1]
	s_add_i32 m0, s75, 0x3800
	v_mfma_f32_16x16x32_bf16 v[124:127], v[100:103], v[116:119], v[124:127]
	global_load_lds_dwordx4 v39, s[0:1]
	s_add_i32 m0, s75, 0x3c00
	v_mfma_f32_16x16x32_bf16 v[124:127], v[104:107], v[120:123], v[124:127]
	global_load_lds_dwordx4 v40, s[0:1]
	s_add_i32 m0, s75, 0x4000
	s_nop 0
	global_load_lds_dwordx4 v41, s[0:1]
	s_nop 5
	s_mov_b64 exec, 0xffff
	ds_write_b128 v86, v[124:127] offset:2048
	s_mov_b64 exec, -1
	s_waitcnt vmcnt(8)
	ds_read_b128 v[108:111], v74 offset:5120
	ds_read_b128 v[112:115], v75 offset:5120
	ds_read_b128 v[116:119], v76 offset:5120
	ds_read_b128 v[120:123], v77 offset:5120
	s_waitcnt lgkmcnt(0)
	v_mfma_f32_16x16x32_bf16 v[124:127], v[92:95], v[108:111], 0
	s_add_i32 m0, s75, 0x1400
	v_mfma_f32_16x16x32_bf16 v[124:127], v[96:99], v[112:115], v[124:127]
	global_load_lds_dwordx4 v42, s[0:1]
	s_add_i32 m0, s75, 0x1800
	v_mfma_f32_16x16x32_bf16 v[124:127], v[100:103], v[116:119], v[124:127]
	global_load_lds_dwordx4 v43, s[0:1]
	s_add_i32 m0, s75, 0x1c00
	v_mfma_f32_16x16x32_bf16 v[124:127], v[104:107], v[120:123], v[124:127]
	global_load_lds_dwordx4 v44, s[0:1]
	s_add_i32 m0, s75, 0x2000
	s_nop 0
	global_load_lds_dwordx4 v45, s[0:1]
	s_nop 5
	s_mov_b64 exec, 0xffff
	ds_write_b128 v86, v[124:127] offset:2304
	s_mov_b64 exec, -1
	s_waitcnt vmcnt(8)
	ds_read_b128 v[108:111], v74 offset:9216
	ds_read_b128 v[112:115], v75 offset:9216
	ds_read_b128 v[116:119], v76 offset:9216
	ds_read_b128 v[120:123], v77 offset:9216
	s_waitcnt lgkmcnt(0)
	v_mfma_f32_16x16x32_bf16 v[124:127], v[92:95], v[108:111], 0
	s_add_i32 m0, s75, 0x2400
	v_mfma_f32_16x16x32_bf16 v[124:127], v[96:99], v[112:115], v[124:127]
	global_load_lds_dwordx4 v46, s[0:1]
	s_add_i32 m0, s75, 0x2800
	v_mfma_f32_16x16x32_bf16 v[124:127], v[100:103], v[116:119], v[124:127]
	global_load_lds_dwordx4 v47, s[0:1]
	s_add_i32 m0, s75, 0x2c00
	v_mfma_f32_16x16x32_bf16 v[124:127], v[104:107], v[120:123], v[124:127]
	global_load_lds_dwordx4 v48, s[0:1]
	s_add_i32 m0, s75, 0x3000
	s_nop 0
	global_load_lds_dwordx4 v49, s[0:1]
	s_nop 5
	s_mov_b64 exec, 0xffff
	ds_write_b128 v86, v[124:127] offset:2560
	s_mov_b64 exec, -1
	s_waitcnt vmcnt(8)
	ds_read_b128 v[108:111], v74 offset:13312
	ds_read_b128 v[112:115], v75 offset:13312
	ds_read_b128 v[116:119], v76 offset:13312
	ds_read_b128 v[120:123], v77 offset:13312
	s_waitcnt lgkmcnt(0)
	v_mfma_f32_16x16x32_bf16 v[124:127], v[92:95], v[108:111], 0
	s_add_i32 m0, s75, 0x3400
	v_mfma_f32_16x16x32_bf16 v[124:127], v[96:99], v[112:115], v[124:127]
	global_load_lds_dwordx4 v50, s[0:1]
	s_add_i32 m0, s75, 0x3800
	v_mfma_f32_16x16x32_bf16 v[124:127], v[100:103], v[116:119], v[124:127]
	global_load_lds_dwordx4 v51, s[0:1]
	s_add_i32 m0, s75, 0x3c00
	v_mfma_f32_16x16x32_bf16 v[124:127], v[104:107], v[120:123], v[124:127]
	global_load_lds_dwordx4 v52, s[0:1]
	s_add_i32 m0, s75, 0x4000
	s_nop 0
	global_load_lds_dwordx4 v53, s[0:1]
	s_nop 5
	s_mov_b64 exec, 0xffff
	ds_write_b128 v86, v[124:127] offset:2816
	s_mov_b64 exec, -1
	s_waitcnt vmcnt(8)
	ds_read_b128 v[108:111], v74 offset:5120
	ds_read_b128 v[112:115], v75 offset:5120
	ds_read_b128 v[116:119], v76 offset:5120
	ds_read_b128 v[120:123], v77 offset:5120
	s_waitcnt lgkmcnt(0)
	v_mfma_f32_16x16x32_bf16 v[124:127], v[92:95], v[108:111], 0
	s_add_i32 m0, s75, 0x1400
	v_mfma_f32_16x16x32_bf16 v[124:127], v[96:99], v[112:115], v[124:127]
	global_load_lds_dwordx4 v54, s[0:1]
	s_add_i32 m0, s75, 0x1800
	v_mfma_f32_16x16x32_bf16 v[124:127], v[100:103], v[116:119], v[124:127]
	global_load_lds_dwordx4 v55, s[0:1]
	s_add_i32 m0, s75, 0x1c00
	v_mfma_f32_16x16x32_bf16 v[124:127], v[104:107], v[120:123], v[124:127]
	global_load_lds_dwordx4 v56, s[0:1]
	s_add_i32 m0, s75, 0x2000
	s_nop 0
	global_load_lds_dwordx4 v57, s[0:1]
	s_nop 5
	s_mov_b64 exec, 0xffff
	ds_write_b128 v86, v[124:127] offset:3072
	s_mov_b64 exec, -1
	s_waitcnt vmcnt(8)
	ds_read_b128 v[108:111], v74 offset:9216
	ds_read_b128 v[112:115], v75 offset:9216
	ds_read_b128 v[116:119], v76 offset:9216
	ds_read_b128 v[120:123], v77 offset:9216
	s_waitcnt lgkmcnt(0)
	v_mfma_f32_16x16x32_bf16 v[124:127], v[92:95], v[108:111], 0
	s_add_i32 m0, s75, 0x2400
	v_mfma_f32_16x16x32_bf16 v[124:127], v[96:99], v[112:115], v[124:127]
	global_load_lds_dwordx4 v58, s[0:1]
	s_add_i32 m0, s75, 0x2800
	v_mfma_f32_16x16x32_bf16 v[124:127], v[100:103], v[116:119], v[124:127]
	global_load_lds_dwordx4 v59, s[0:1]
	s_add_i32 m0, s75, 0x2c00
	v_mfma_f32_16x16x32_bf16 v[124:127], v[104:107], v[120:123], v[124:127]
	global_load_lds_dwordx4 v60, s[0:1]
	s_add_i32 m0, s75, 0x3000
	s_nop 0
	global_load_lds_dwordx4 v61, s[0:1]
	s_nop 5
	s_mov_b64 exec, 0xffff
	ds_write_b128 v86, v[124:127] offset:3328
	s_mov_b64 exec, -1
	s_waitcnt vmcnt(8)
	ds_read_b128 v[108:111], v74 offset:13312
	ds_read_b128 v[112:115], v75 offset:13312
	ds_read_b128 v[116:119], v76 offset:13312
	ds_read_b128 v[120:123], v77 offset:13312
	s_waitcnt lgkmcnt(0)
	v_mfma_f32_16x16x32_bf16 v[124:127], v[92:95], v[108:111], 0
	s_add_i32 m0, s75, 0x3400
	v_mfma_f32_16x16x32_bf16 v[124:127], v[96:99], v[112:115], v[124:127]
	global_load_lds_dwordx4 v62, s[0:1]
	s_add_i32 m0, s75, 0x3800
	v_mfma_f32_16x16x32_bf16 v[124:127], v[100:103], v[116:119], v[124:127]
	global_load_lds_dwordx4 v63, s[0:1]
	s_add_i32 m0, s75, 0x3c00
	v_mfma_f32_16x16x32_bf16 v[124:127], v[104:107], v[120:123], v[124:127]
	global_load_lds_dwordx4 v64, s[0:1]
	s_add_i32 m0, s75, 0x4000
	s_nop 0
	global_load_lds_dwordx4 v65, s[0:1]
	s_nop 5
	s_mov_b64 exec, 0xffff
	ds_write_b128 v86, v[124:127] offset:3584
	s_mov_b64 exec, -1
	s_waitcnt vmcnt(8)
	ds_read_b128 v[108:111], v74 offset:5120
	ds_read_b128 v[112:115], v75 offset:5120
	ds_read_b128 v[116:119], v76 offset:5120
	ds_read_b128 v[120:123], v77 offset:5120
	s_waitcnt lgkmcnt(0)
	v_mfma_f32_16x16x32_bf16 v[124:127], v[92:95], v[108:111], 0
	s_add_i32 m0, s75, 0x1400
	v_mfma_f32_16x16x32_bf16 v[124:127], v[96:99], v[112:115], v[124:127]
	global_load_lds_dwordx4 v66, s[0:1]
	s_add_i32 m0, s75, 0x1800
	v_mfma_f32_16x16x32_bf16 v[124:127], v[100:103], v[116:119], v[124:127]
	global_load_lds_dwordx4 v67, s[0:1]
	s_add_i32 m0, s75, 0x1c00
	v_mfma_f32_16x16x32_bf16 v[124:127], v[104:107], v[120:123], v[124:127]
	global_load_lds_dwordx4 v68, s[0:1]
	s_add_i32 m0, s75, 0x2000
	s_nop 0
	global_load_lds_dwordx4 v69, s[0:1]
	s_nop 5
	s_mov_b64 exec, 0xffff
	ds_write_b128 v86, v[124:127] offset:3840
	s_mov_b64 exec, -1
	s_waitcnt vmcnt(8)
	ds_read_b128 v[108:111], v74 offset:9216
	ds_read_b128 v[112:115], v75 offset:9216
	ds_read_b128 v[116:119], v76 offset:9216
	ds_read_b128 v[120:123], v77 offset:9216
	s_waitcnt lgkmcnt(0)
	v_mfma_f32_16x16x32_bf16 v[124:127], v[92:95], v[108:111], 0
	s_add_i32 m0, s75, 0x2400
	v_mfma_f32_16x16x32_bf16 v[124:127], v[96:99], v[112:115], v[124:127]
	global_load_lds_dwordx4 v70, s[0:1]
	s_add_i32 m0, s75, 0x2800
	v_mfma_f32_16x16x32_bf16 v[124:127], v[100:103], v[116:119], v[124:127]
	global_load_lds_dwordx4 v71, s[0:1]
	s_add_i32 m0, s75, 0x2c00
	v_mfma_f32_16x16x32_bf16 v[124:127], v[104:107], v[120:123], v[124:127]
	global_load_lds_dwordx4 v72, s[0:1]
	s_add_i32 m0, s75, 0x3000
	s_nop 0
	global_load_lds_dwordx4 v73, s[0:1]
	s_nop 5
	s_mov_b64 exec, 0xffff
	ds_write_b128 v86, v[124:127] offset:4096
	s_mov_b64 exec, -1
	s_waitcnt vmcnt(8)
	ds_read_b128 v[108:111], v74 offset:13312
	ds_read_b128 v[112:115], v75 offset:13312
	ds_read_b128 v[116:119], v76 offset:13312
	ds_read_b128 v[120:123], v77 offset:13312
	s_waitcnt lgkmcnt(0)
	v_mfma_f32_16x16x32_bf16 v[124:127], v[92:95], v[108:111], 0
	v_mfma_f32_16x16x32_bf16 v[124:127], v[96:99], v[112:115], v[124:127]
	v_mfma_f32_16x16x32_bf16 v[124:127], v[100:103], v[116:119], v[124:127]
	v_mfma_f32_16x16x32_bf16 v[124:127], v[104:107], v[120:123], v[124:127]
	s_nop 7
	s_nop 0
	s_mov_b64 exec, 0xffff
	ds_write_b128 v86, v[124:127] offset:4352
	s_mov_b64 exec, -1
	s_waitcnt vmcnt(4)
	ds_read_b128 v[108:111], v74 offset:5120
	ds_read_b128 v[112:115], v75 offset:5120
	ds_read_b128 v[116:119], v76 offset:5120
	ds_read_b128 v[120:123], v77 offset:5120
	s_waitcnt lgkmcnt(0)
	v_mfma_f32_16x16x32_bf16 v[124:127], v[92:95], v[108:111], 0
	v_mfma_f32_16x16x32_bf16 v[124:127], v[96:99], v[112:115], v[124:127]
	v_mfma_f32_16x16x32_bf16 v[124:127], v[100:103], v[116:119], v[124:127]
	v_mfma_f32_16x16x32_bf16 v[124:127], v[104:107], v[120:123], v[124:127]
	s_nop 7
	s_nop 0
	s_mov_b64 exec, 0xffff
	ds_write_b128 v86, v[124:127] offset:4608
	s_mov_b64 exec, -1
	s_waitcnt vmcnt(0)
	ds_read_b128 v[108:111], v74 offset:9216
	ds_read_b128 v[112:115], v75 offset:9216
	ds_read_b128 v[116:119], v76 offset:9216
	ds_read_b128 v[120:123], v77 offset:9216
	s_waitcnt lgkmcnt(0)
	v_mfma_f32_16x16x32_bf16 v[124:127], v[92:95], v[108:111], 0
	v_mfma_f32_16x16x32_bf16 v[124:127], v[96:99], v[112:115], v[124:127]
	v_mfma_f32_16x16x32_bf16 v[124:127], v[100:103], v[116:119], v[124:127]
	v_mfma_f32_16x16x32_bf16 v[124:127], v[104:107], v[120:123], v[124:127]
	s_nop 7
	s_nop 0
	s_mov_b64 exec, 0xffff
	ds_write_b128 v86, v[124:127] offset:4864
	s_mov_b64 exec, -1
	s_add_i32 m0, s75, 0x2400
	s_nop 0
	global_load_lds_dwordx4 v10, s[2:3]
	s_add_i32 m0, s75, 0x2800
	s_nop 0
	global_load_lds_dwordx4 v11, s[2:3]
	s_add_i32 m0, s75, 0x2c00
	s_nop 0
	global_load_lds_dwordx4 v12, s[2:3]
	s_add_i32 m0, s75, 0x3000
	s_nop 0
	global_load_lds_dwordx4 v13, s[2:3]
	s_add_i32 m0, s75, 0x3400
	s_nop 0
	global_load_lds_dwordx4 v14, s[2:3]
	s_add_i32 m0, s75, 0x3800
	s_nop 0
	global_load_lds_dwordx4 v15, s[2:3]
	s_add_i32 m0, s75, 0x3c00
	s_nop 0
	global_load_lds_dwordx4 v16, s[2:3]
	s_add_i32 m0, s75, 0x4000
	s_nop 0
	global_load_lds_dwordx4 v17, s[2:3]
	s_waitcnt lgkmcnt(0)
	ds_read_b128 v[108:111], v87 offset:1024
	ds_read_b128 v[112:115], v87 offset:2048
	ds_read_b128 v[116:119], v87 offset:3072
	ds_read_b128 v[120:123], v87 offset:4096
	s_waitcnt lgkmcnt(0)
	s_add_i32 m0, s75, 0x400
	s_nop 0
	global_load_lds_dwordx4 v18, s[2:3]
	s_add_i32 m0, s75, 0x800
	s_nop 0
	global_load_lds_dwordx4 v19, s[2:3]
	s_add_i32 m0, s75, 0xc00
	s_nop 0
	global_load_lds_dwordx4 v20, s[2:3]
	s_add_i32 m0, s75, 0x1000
	s_nop 0
	global_load_lds_dwordx4 v21, s[2:3]
	s_add_i32 m0, s75, 0x1400
	s_nop 0
	global_load_lds_dwordx4 v22, s[2:3]
	s_add_i32 m0, s75, 0x1800
	s_nop 0
	global_load_lds_dwordx4 v23, s[2:3]
	s_add_i32 m0, s75, 0x1c00
	s_nop 0
	global_load_lds_dwordx4 v24, s[2:3]
	s_add_i32 m0, s75, 0x2000
	s_nop 0
	global_load_lds_dwordx4 v25, s[2:3]
	s_cmp_eq_u32 s73, 0x100
	s_cbranch_scc1 .Lau_nomask1_1
	v_mov_b32_e32 v9, 0xff61b1e6
	v_cndmask_b32_e64 v108, v9, v108, s[24:25]
	v_cndmask_b32_e64 v109, v9, v109, s[24:25]
	v_cndmask_b32_e64 v110, v9, v110, s[24:25]
	v_cndmask_b32_e64 v111, v9, v111, s[24:25]
	v_cndmask_b32_e64 v112, v9, v112, s[26:27]
	v_cndmask_b32_e64 v113, v9, v113, s[26:27]
	v_cndmask_b32_e64 v114, v9, v114, s[26:27]
	v_cndmask_b32_e64 v115, v9, v115, s[26:27]
	v_cndmask_b32_e64 v116, v9, v116, s[28:29]
	v_cndmask_b32_e64 v117, v9, v117, s[28:29]
	v_cndmask_b32_e64 v118, v9, v118, s[28:29]
	v_cndmask_b32_e64 v119, v9, v119, s[28:29]
	v_cndmask_b32_e64 v120, v9, v120, s[30:31]
	v_cndmask_b32_e64 v121, v9, v121, s[30:31]
	v_cndmask_b32_e64 v122, v9, v122, s[30:31]
	v_cndmask_b32_e64 v123, v9, v123, s[30:31]

.Lau_nomask2_1:
	s_nop 0
	v_add_f32_e32 v216, 0, v108
	v_add_f32_e32 v217, 0, v109
	v_add_f32_e32 v218, 0, v110
	v_add_f32_e32 v219, 0, v111
	v_add_f32_e32 v216, v112, v216
	v_add_f32_e32 v217, v113, v217
	v_add_f32_e32 v218, v114, v218
	v_add_f32_e32 v219, v115, v219
	v_add_f32_e32 v216, v116, v216
	v_add_f32_e32 v217, v117, v217
	v_add_f32_e32 v218, v118, v218
	v_add_f32_e32 v219, v119, v219
	v_add_f32_e32 v216, v120, v216
	v_add_f32_e32 v217, v121, v217
	v_add_f32_e32 v218, v122, v218
	v_add_f32_e32 v219, v123, v219
	v_add_f32_dpp v216, v216, v216 quad_perm:[1,0,3,2] row_mask:0xf bank_mask:0xf bound_ctrl:1
	v_add_f32_dpp v217, v217, v217 quad_perm:[1,0,3,2] row_mask:0xf bank_mask:0xf bound_ctrl:1
	v_add_f32_dpp v218, v218, v218 quad_perm:[1,0,3,2] row_mask:0xf bank_mask:0xf bound_ctrl:1
	v_add_f32_dpp v219, v219, v219 quad_perm:[1,0,3,2] row_mask:0xf bank_mask:0xf bound_ctrl:1
	v_add_f32_dpp v216, v216, v216 quad_perm:[2,3,0,1] row_mask:0xf bank_mask:0xf bound_ctrl:1
	v_add_f32_dpp v217, v217, v217 quad_perm:[2,3,0,1] row_mask:0xf bank_mask:0xf bound_ctrl:1
	v_add_f32_dpp v218, v218, v218 quad_perm:[2,3,0,1] row_mask:0xf bank_mask:0xf bound_ctrl:1
	v_add_f32_dpp v219, v219, v219 quad_perm:[2,3,0,1] row_mask:0xf bank_mask:0xf bound_ctrl:1
	v_add_f32_dpp v216, v216, v216 row_half_mirror row_mask:0xf bank_mask:0xf bound_ctrl:1
	v_add_f32_dpp v217, v217, v217 row_half_mirror row_mask:0xf bank_mask:0xf bound_ctrl:1
	v_add_f32_dpp v218, v218, v218 row_half_mirror row_mask:0xf bank_mask:0xf bound_ctrl:1
	v_add_f32_dpp v219, v219, v219 row_half_mirror row_mask:0xf bank_mask:0xf bound_ctrl:1
	v_add_f32_dpp v216, v216, v216 row_mirror row_mask:0xf bank_mask:0xf bound_ctrl:1
	v_add_f32_dpp v217, v217, v217 row_mirror row_mask:0xf bank_mask:0xf bound_ctrl:1
	v_add_f32_dpp v218, v218, v218 row_mirror row_mask:0xf bank_mask:0xf bound_ctrl:1
	v_add_f32_dpp v219, v219, v219 row_mirror row_mask:0xf bank_mask:0xf bound_ctrl:1
	v_add_f32_dpp v216, v216, v216 row_bcast:15 row_mask:0xa bank_mask:0xf
	v_add_f32_dpp v217, v217, v217 row_bcast:15 row_mask:0xa bank_mask:0xf
	v_add_f32_dpp v218, v218, v218 row_bcast:15 row_mask:0xa bank_mask:0xf
	v_add_f32_dpp v219, v219, v219 row_bcast:15 row_mask:0xa bank_mask:0xf
	v_add_f32_dpp v216, v216, v216 row_bcast:31 row_mask:0xc bank_mask:0xf
	v_add_f32_dpp v217, v217, v217 row_bcast:31 row_mask:0xc bank_mask:0xf
	v_add_f32_dpp v218, v218, v218 row_bcast:31 row_mask:0xc bank_mask:0xf
	v_add_f32_dpp v219, v219, v219 row_bcast:31 row_mask:0xc bank_mask:0xf
	s_nop 0
	v_readlane_b32 s84, v216, 63
	v_readlane_b32 s85, v217, 63
	v_readlane_b32 s86, v218, 63
	v_readlane_b32 s87, v219, 63
	s_nop 1
	v_mov_b32_e32 v216, s84
	v_mov_b32_e32 v217, s85
	v_mov_b32_e32 v218, s86
	v_mov_b32_e32 v219, s87
	v_div_scale_f32 v220, s[8:9], v216, v216, 1.0
	v_div_scale_f32 v221, s[8:9], v217, v217, 1.0
	v_div_scale_f32 v222, s[8:9], v218, v218, 1.0
	v_div_scale_f32 v223, s[8:9], v219, v219, 1.0
	v_rcp_f32_e32 v128, v220
	v_rcp_f32_e32 v129, v221
	v_rcp_f32_e32 v130, v222
	v_rcp_f32_e32 v131, v223
	s_nop 0
	v_fma_f32 v124, -v220, v128, 1.0
	v_fma_f32 v125, -v221, v129, 1.0
	v_fma_f32 v126, -v222, v130, 1.0
	v_fma_f32 v127, -v223, v131, 1.0
	v_fmac_f32_e32 v128, v124, v128
	v_fmac_f32_e32 v129, v125, v129
	v_fmac_f32_e32 v130, v126, v130
	v_fmac_f32_e32 v131, v127, v131
	v_div_scale_f32 v224, vcc, 1.0, v216, 1.0
	v_mul_f32_e32 v225, v224, v128
	v_fma_f32 v134, -v220, v225, v224
	v_fmac_f32_e32 v225, v134, v128
	v_fma_f32 v220, -v220, v225, v224
	s_nop 0
	v_div_fmas_f32 v220, v220, v128, v225
	v_div_fixup_f32 v220, v220, v216, 1.0
	v_div_scale_f32 v224, vcc, 1.0, v217, 1.0
	v_mul_f32_e32 v225, v224, v129
	v_fma_f32 v134, -v221, v225, v224
	v_fmac_f32_e32 v225, v134, v129
	v_fma_f32 v221, -v221, v225, v224
	s_nop 0
	v_div_fmas_f32 v221, v221, v129, v225
	v_div_fixup_f32 v221, v221, v217, 1.0
	v_div_scale_f32 v224, vcc, 1.0, v218, 1.0
	v_mul_f32_e32 v225, v224, v130
	v_fma_f32 v134, -v222, v225, v224
	v_fmac_f32_e32 v225, v134, v130
	v_fma_f32 v222, -v222, v225, v224
	s_nop 0
	v_div_fmas_f32 v222, v222, v130, v225
	v_div_fixup_f32 v222, v222, v218, 1.0
	v_div_scale_f32 v224, vcc, 1.0, v219, 1.0
	v_mul_f32_e32 v225, v224, v131
	v_fma_f32 v134, -v223, v225, v224
	v_fmac_f32_e32 v225, v134, v131
	v_fma_f32 v223, -v223, v225, v224
	s_nop 0
	v_div_fmas_f32 v223, v223, v131, v225
	v_div_fixup_f32 v223, v223, v219, 1.0
	v_mul_f32_e32 v108, v108, v220
	v_mul_f32_e32 v109, v109, v221
	v_mul_f32_e32 v110, v110, v222
	v_mul_f32_e32 v111, v111, v223
	v_mul_f32_e32 v112, v112, v220
	v_mul_f32_e32 v113, v113, v221
	v_mul_f32_e32 v114, v114, v222
	v_mul_f32_e32 v115, v115, v223
	v_mul_f32_e32 v116, v116, v220
	v_mul_f32_e32 v117, v117, v221
	v_mul_f32_e32 v118, v118, v222
	v_mul_f32_e32 v119, v119, v223
	v_mul_f32_e32 v120, v120, v220
	v_mul_f32_e32 v121, v121, v221
	v_mul_f32_e32 v122, v122, v222
	v_mul_f32_e32 v123, v123, v223
	v_cvt_pk_bf16_f32 v108, v108, v108
	v_cvt_pk_bf16_f32 v109, v109, v109
	v_cvt_pk_bf16_f32 v110, v110, v110
	v_cvt_pk_bf16_f32 v111, v111, v111
	v_cvt_pk_bf16_f32 v112, v112, v112
	v_cvt_pk_bf16_f32 v113, v113, v113
	v_cvt_pk_bf16_f32 v114, v114, v114
	v_cvt_pk_bf16_f32 v115, v115, v115
	v_cvt_pk_bf16_f32 v116, v116, v116
	v_cvt_pk_bf16_f32 v117, v117, v117
	v_cvt_pk_bf16_f32 v118, v118, v118
	v_cvt_pk_bf16_f32 v119, v119, v119
	v_cvt_pk_bf16_f32 v120, v120, v120
	v_cvt_pk_bf16_f32 v121, v121, v121
	v_cvt_pk_bf16_f32 v122, v122, v122
	v_cvt_pk_bf16_f32 v123, v123, v123
	ds_write_b16 v88, v108 offset:0
	ds_write_b16 v88, v109 offset:512
	ds_write_b16 v88, v110 offset:1024
	ds_write_b16 v88, v111 offset:1536
	ds_write_b16 v88, v112 offset:128
	ds_write_b16 v88, v113 offset:640
	ds_write_b16 v88, v114 offset:1152
	ds_write_b16 v88, v115 offset:1664
	ds_write_b16 v88, v116 offset:256
	ds_write_b16 v88, v117 offset:768
	ds_write_b16 v88, v118 offset:1280
	ds_write_b16 v88, v119 offset:1792
	ds_write_b16 v88, v120 offset:384
	ds_write_b16 v88, v121 offset:896
	ds_write_b16 v88, v122 offset:1408
	ds_write_b16 v88, v123 offset:1920
	s_waitcnt vmcnt(8)
	s_waitcnt lgkmcnt(0)
	ds_read_b128 v[172:175], v89 offset:0
	ds_read_b64_tr_b16 v[140:141], v78 offset:9216
	ds_read_b64_tr_b16 v[142:143], v78 offset:10240
	ds_read_b64_tr_b16 v[144:145], v79 offset:9216
	ds_read_b64_tr_b16 v[146:147], v79 offset:10240
	ds_read_b64_tr_b16 v[148:149], v80 offset:9216
	ds_read_b64_tr_b16 v[150:151], v80 offset:10240
	ds_read_b64_tr_b16 v[152:153], v81 offset:9216
	ds_read_b64_tr_b16 v[154:155], v81 offset:10240
	ds_read_b64_tr_b16 v[156:157], v82 offset:9216
	ds_read_b64_tr_b16 v[158:159], v82 offset:10240
	ds_read_b64_tr_b16 v[160:161], v83 offset:9216
	ds_read_b64_tr_b16 v[162:163], v83 offset:10240
	ds_read_b64_tr_b16 v[164:165], v84 offset:9216
	ds_read_b64_tr_b16 v[166:167], v84 offset:10240
	ds_read_b64_tr_b16 v[168:169], v85 offset:9216
	ds_read_b64_tr_b16 v[170:171], v85 offset:10240
	s_waitcnt lgkmcnt(0)
	v_mfma_f32_16x16x32_bf16 v[184:187], v[172:175], v[140:143], 0
	s_add_i32 m0, s75, 0x2400
	v_mfma_f32_16x16x32_bf16 v[188:191], v[172:175], v[144:147], 0
	global_load_lds_dwordx4 v26, s[2:3]
	s_add_i32 m0, s75, 0x2800
	v_mfma_f32_16x16x32_bf16 v[192:195], v[172:175], v[148:151], 0
	global_load_lds_dwordx4 v27, s[2:3]
	s_add_i32 m0, s75, 0x2c00
	v_mfma_f32_16x16x32_bf16 v[196:199], v[172:175], v[152:155], 0
	global_load_lds_dwordx4 v28, s[2:3]
	s_add_i32 m0, s75, 0x3000
	v_mfma_f32_16x16x32_bf16 v[200:203], v[172:175], v[156:159], 0
	global_load_lds_dwordx4 v29, s[2:3]
	s_add_i32 m0, s75, 0x3400
	v_mfma_f32_16x16x32_bf16 v[204:207], v[172:175], v[160:163], 0
	global_load_lds_dwordx4 v30, s[2:3]
	s_add_i32 m0, s75, 0x3800
	v_mfma_f32_16x16x32_bf16 v[208:211], v[172:175], v[164:167], 0
	global_load_lds_dwordx4 v31, s[2:3]
	s_add_i32 m0, s75, 0x3c00
	v_mfma_f32_16x16x32_bf16 v[212:215], v[172:175], v[168:171], 0
	global_load_lds_dwordx4 v32, s[2:3]
	s_add_i32 m0, s75, 0x4000
	s_nop 0
	global_load_lds_dwordx4 v33, s[2:3]
	s_waitcnt vmcnt(8)
	ds_read_b128 v[172:175], v89 offset:64
	ds_read_b64_tr_b16 v[140:141], v78 offset:1024
	ds_read_b64_tr_b16 v[142:143], v78 offset:2048
	ds_read_b64_tr_b16 v[144:145], v79 offset:1024
	ds_read_b64_tr_b16 v[146:147], v79 offset:2048
	ds_read_b64_tr_b16 v[148:149], v80 offset:1024
	ds_read_b64_tr_b16 v[150:151], v80 offset:2048
	ds_read_b64_tr_b16 v[152:153], v81 offset:1024
	ds_read_b64_tr_b16 v[154:155], v81 offset:2048
	ds_read_b64_tr_b16 v[156:157], v82 offset:1024
	ds_read_b64_tr_b16 v[158:159], v82 offset:2048
	ds_read_b64_tr_b16 v[160:161], v83 offset:1024
	ds_read_b64_tr_b16 v[162:163], v83 offset:2048
	ds_read_b64_tr_b16 v[164:165], v84 offset:1024
	ds_read_b64_tr_b16 v[166:167], v84 offset:2048
	ds_read_b64_tr_b16 v[168:169], v85 offset:1024
	ds_read_b64_tr_b16 v[170:171], v85 offset:2048
	s_waitcnt lgkmcnt(0)
	v_mfma_f32_16x16x32_bf16 v[184:187], v[172:175], v[140:143], v[184:187]
	s_add_i32 m0, s75, 0x400
	v_mfma_f32_16x16x32_bf16 v[188:191], v[172:175], v[144:147], v[188:191]
	global_load_lds_dwordx4 v34, s[2:3]
	s_add_i32 m0, s75, 0x800
	v_mfma_f32_16x16x32_bf16 v[192:195], v[172:175], v[148:151], v[192:195]
	global_load_lds_dwordx4 v35, s[2:3]
	s_add_i32 m0, s75, 0xc00
	v_mfma_f32_16x16x32_bf16 v[196:199], v[172:175], v[152:155], v[196:199]
	global_load_lds_dwordx4 v36, s[2:3]
	s_add_i32 m0, s75, 0x1000
	v_mfma_f32_16x16x32_bf16 v[200:203], v[172:175], v[156:159], v[200:203]
	global_load_lds_dwordx4 v37, s[2:3]
	s_add_i32 m0, s75, 0x1400
	v_mfma_f32_16x16x32_bf16 v[204:207], v[172:175], v[160:163], v[204:207]
	global_load_lds_dwordx4 v38, s[2:3]
	s_add_i32 m0, s75, 0x1800
	v_mfma_f32_16x16x32_bf16 v[208:211], v[172:175], v[164:167], v[208:211]
	global_load_lds_dwordx4 v39, s[2:3]
	s_add_i32 m0, s75, 0x1c00
	v_mfma_f32_16x16x32_bf16 v[212:215], v[172:175], v[168:171], v[212:215]
	global_load_lds_dwordx4 v40, s[2:3]
	s_add_i32 m0, s75, 0x2000
	s_nop 0
	global_load_lds_dwordx4 v41, s[2:3]
	s_waitcnt vmcnt(8)
	ds_read_b128 v[172:175], v89 offset:128
	ds_read_b64_tr_b16 v[140:141], v78 offset:9216
	ds_read_b64_tr_b16 v[142:143], v78 offset:10240
	ds_read_b64_tr_b16 v[144:145], v79 offset:9216
	ds_read_b64_tr_b16 v[146:147], v79 offset:10240
	ds_read_b64_tr_b16 v[148:149], v80 offset:9216
	ds_read_b64_tr_b16 v[150:151], v80 offset:10240
	ds_read_b64_tr_b16 v[152:153], v81 offset:9216
	ds_read_b64_tr_b16 v[154:155], v81 offset:10240
	ds_read_b64_tr_b16 v[156:157], v82 offset:9216
	ds_read_b64_tr_b16 v[158:159], v82 offset:10240
	ds_read_b64_tr_b16 v[160:161], v83 offset:9216
	ds_read_b64_tr_b16 v[162:163], v83 offset:10240
	ds_read_b64_tr_b16 v[164:165], v84 offset:9216
	ds_read_b64_tr_b16 v[166:167], v84 offset:10240
	ds_read_b64_tr_b16 v[168:169], v85 offset:9216
	ds_read_b64_tr_b16 v[170:171], v85 offset:10240
	s_waitcnt lgkmcnt(0)
	v_mfma_f32_16x16x32_bf16 v[184:187], v[172:175], v[140:143], v[184:187]
	s_add_i32 m0, s75, 0x2400
	v_mfma_f32_16x16x32_bf16 v[188:191], v[172:175], v[144:147], v[188:191]
	global_load_lds_dwordx4 v42, s[2:3]
	s_add_i32 m0, s75, 0x2800
	v_mfma_f32_16x16x32_bf16 v[192:195], v[172:175], v[148:151], v[192:195]
	global_load_lds_dwordx4 v43, s[2:3]
	s_add_i32 m0, s75, 0x2c00
	v_mfma_f32_16x16x32_bf16 v[196:199], v[172:175], v[152:155], v[196:199]
	global_load_lds_dwordx4 v44, s[2:3]
	s_add_i32 m0, s75, 0x3000
	v_mfma_f32_16x16x32_bf16 v[200:203], v[172:175], v[156:159], v[200:203]
	global_load_lds_dwordx4 v45, s[2:3]
	s_add_i32 m0, s75, 0x3400
	v_mfma_f32_16x16x32_bf16 v[204:207], v[172:175], v[160:163], v[204:207]
	global_load_lds_dwordx4 v46, s[2:3]
	s_add_i32 m0, s75, 0x3800
	v_mfma_f32_16x16x32_bf16 v[208:211], v[172:175], v[164:167], v[208:211]
	global_load_lds_dwordx4 v47, s[2:3]
	s_add_i32 m0, s75, 0x3c00
	v_mfma_f32_16x16x32_bf16 v[212:215], v[172:175], v[168:171], v[212:215]
	global_load_lds_dwordx4 v48, s[2:3]
	s_add_i32 m0, s75, 0x4000
	s_nop 0
	global_load_lds_dwordx4 v49, s[2:3]
	s_waitcnt vmcnt(8)
	ds_read_b128 v[172:175], v89 offset:192
	ds_read_b64_tr_b16 v[140:141], v78 offset:1024
	ds_read_b64_tr_b16 v[142:143], v78 offset:2048
	ds_read_b64_tr_b16 v[144:145], v79 offset:1024
	ds_read_b64_tr_b16 v[146:147], v79 offset:2048
	ds_read_b64_tr_b16 v[148:149], v80 offset:1024
	ds_read_b64_tr_b16 v[150:151], v80 offset:2048
	ds_read_b64_tr_b16 v[152:153], v81 offset:1024
	ds_read_b64_tr_b16 v[154:155], v81 offset:2048
	ds_read_b64_tr_b16 v[156:157], v82 offset:1024
	ds_read_b64_tr_b16 v[158:159], v82 offset:2048
	ds_read_b64_tr_b16 v[160:161], v83 offset:1024
	ds_read_b64_tr_b16 v[162:163], v83 offset:2048
	ds_read_b64_tr_b16 v[164:165], v84 offset:1024
	ds_read_b64_tr_b16 v[166:167], v84 offset:2048
	ds_read_b64_tr_b16 v[168:169], v85 offset:1024
	ds_read_b64_tr_b16 v[170:171], v85 offset:2048
	s_waitcnt lgkmcnt(0)
	v_mfma_f32_16x16x32_bf16 v[184:187], v[172:175], v[140:143], v[184:187]
	s_add_i32 m0, s75, 0x400
	v_mfma_f32_16x16x32_bf16 v[188:191], v[172:175], v[144:147], v[188:191]
	global_load_lds_dwordx4 v50, s[2:3]
	s_add_i32 m0, s75, 0x800
	v_mfma_f32_16x16x32_bf16 v[192:195], v[172:175], v[148:151], v[192:195]
	global_load_lds_dwordx4 v51, s[2:3]
	s_add_i32 m0, s75, 0xc00
	v_mfma_f32_16x16x32_bf16 v[196:199], v[172:175], v[152:155], v[196:199]
	global_load_lds_dwordx4 v52, s[2:3]
	s_add_i32 m0, s75, 0x1000
	v_mfma_f32_16x16x32_bf16 v[200:203], v[172:175], v[156:159], v[200:203]
	global_load_lds_dwordx4 v53, s[2:3]
	s_add_i32 m0, s75, 0x1400
	v_mfma_f32_16x16x32_bf16 v[204:207], v[172:175], v[160:163], v[204:207]
	global_load_lds_dwordx4 v54, s[2:3]
	s_add_i32 m0, s75, 0x1800
	v_mfma_f32_16x16x32_bf16 v[208:211], v[172:175], v[164:167], v[208:211]
	global_load_lds_dwordx4 v55, s[2:3]
	s_add_i32 m0, s75, 0x1c00
	v_mfma_f32_16x16x32_bf16 v[212:215], v[172:175], v[168:171], v[212:215]
	global_load_lds_dwordx4 v56, s[2:3]
	s_add_i32 m0, s75, 0x2000
	s_nop 0
	global_load_lds_dwordx4 v57, s[2:3]
	s_waitcnt vmcnt(8)
	ds_read_b128 v[172:175], v89 offset:256
	ds_read_b64_tr_b16 v[140:141], v78 offset:9216
	ds_read_b64_tr_b16 v[142:143], v78 offset:10240
	ds_read_b64_tr_b16 v[144:145], v79 offset:9216
	ds_read_b64_tr_b16 v[146:147], v79 offset:10240
	ds_read_b64_tr_b16 v[148:149], v80 offset:9216
	ds_read_b64_tr_b16 v[150:151], v80 offset:10240
	ds_read_b64_tr_b16 v[152:153], v81 offset:9216
	ds_read_b64_tr_b16 v[154:155], v81 offset:10240
	ds_read_b64_tr_b16 v[156:157], v82 offset:9216
	ds_read_b64_tr_b16 v[158:159], v82 offset:10240
	ds_read_b64_tr_b16 v[160:161], v83 offset:9216
	ds_read_b64_tr_b16 v[162:163], v83 offset:10240
	ds_read_b64_tr_b16 v[164:165], v84 offset:9216
	ds_read_b64_tr_b16 v[166:167], v84 offset:10240
	ds_read_b64_tr_b16 v[168:169], v85 offset:9216
	ds_read_b64_tr_b16 v[170:171], v85 offset:10240
	s_waitcnt lgkmcnt(0)
	v_mfma_f32_16x16x32_bf16 v[184:187], v[172:175], v[140:143], v[184:187]
	s_add_i32 m0, s75, 0x2400
	v_mfma_f32_16x16x32_bf16 v[188:191], v[172:175], v[144:147], v[188:191]
	global_load_lds_dwordx4 v58, s[2:3]
	s_add_i32 m0, s75, 0x2800
	v_mfma_f32_16x16x32_bf16 v[192:195], v[172:175], v[148:151], v[192:195]
	global_load_lds_dwordx4 v59, s[2:3]
	s_add_i32 m0, s75, 0x2c00
	v_mfma_f32_16x16x32_bf16 v[196:199], v[172:175], v[152:155], v[196:199]
	global_load_lds_dwordx4 v60, s[2:3]
	s_add_i32 m0, s75, 0x3000
	v_mfma_f32_16x16x32_bf16 v[200:203], v[172:175], v[156:159], v[200:203]
	global_load_lds_dwordx4 v61, s[2:3]
	s_add_i32 m0, s75, 0x3400
	v_mfma_f32_16x16x32_bf16 v[204:207], v[172:175], v[160:163], v[204:207]
	global_load_lds_dwordx4 v62, s[2:3]
	s_add_i32 m0, s75, 0x3800
	v_mfma_f32_16x16x32_bf16 v[208:211], v[172:175], v[164:167], v[208:211]
	global_load_lds_dwordx4 v63, s[2:3]
	s_add_i32 m0, s75, 0x3c00
	v_mfma_f32_16x16x32_bf16 v[212:215], v[172:175], v[168:171], v[212:215]
	global_load_lds_dwordx4 v64, s[2:3]
	s_add_i32 m0, s75, 0x4000
	s_nop 0
	global_load_lds_dwordx4 v65, s[2:3]
	s_waitcnt vmcnt(8)
	ds_read_b128 v[172:175], v89 offset:320
	ds_read_b64_tr_b16 v[140:141], v78 offset:1024
	ds_read_b64_tr_b16 v[142:143], v78 offset:2048
	ds_read_b64_tr_b16 v[144:145], v79 offset:1024
	ds_read_b64_tr_b16 v[146:147], v79 offset:2048
	ds_read_b64_tr_b16 v[148:149], v80 offset:1024
	ds_read_b64_tr_b16 v[150:151], v80 offset:2048
	ds_read_b64_tr_b16 v[152:153], v81 offset:1024
	ds_read_b64_tr_b16 v[154:155], v81 offset:2048
	ds_read_b64_tr_b16 v[156:157], v82 offset:1024
	ds_read_b64_tr_b16 v[158:159], v82 offset:2048
	ds_read_b64_tr_b16 v[160:161], v83 offset:1024
	ds_read_b64_tr_b16 v[162:163], v83 offset:2048
	ds_read_b64_tr_b16 v[164:165], v84 offset:1024
	ds_read_b64_tr_b16 v[166:167], v84 offset:2048
	ds_read_b64_tr_b16 v[168:169], v85 offset:1024
	ds_read_b64_tr_b16 v[170:171], v85 offset:2048
	s_waitcnt lgkmcnt(0)
	v_mfma_f32_16x16x32_bf16 v[184:187], v[172:175], v[140:143], v[184:187]
	s_add_i32 m0, s75, 0x400
	v_mfma_f32_16x16x32_bf16 v[188:191], v[172:175], v[144:147], v[188:191]
	global_load_lds_dwordx4 v66, s[2:3]
	s_add_i32 m0, s75, 0x800
	v_mfma_f32_16x16x32_bf16 v[192:195], v[172:175], v[148:151], v[192:195]
	global_load_lds_dwordx4 v67, s[2:3]
	s_add_i32 m0, s75, 0xc00
	v_mfma_f32_16x16x32_bf16 v[196:199], v[172:175], v[152:155], v[196:199]
	global_load_lds_dwordx4 v68, s[2:3]
	s_add_i32 m0, s75, 0x1000
	v_mfma_f32_16x16x32_bf16 v[200:203], v[172:175], v[156:159], v[200:203]
	global_load_lds_dwordx4 v69, s[2:3]
	s_add_i32 m0, s75, 0x1400
	v_mfma_f32_16x16x32_bf16 v[204:207], v[172:175], v[160:163], v[204:207]
	global_load_lds_dwordx4 v70, s[2:3]
	s_add_i32 m0, s75, 0x1800
	v_mfma_f32_16x16x32_bf16 v[208:211], v[172:175], v[164:167], v[208:211]
	global_load_lds_dwordx4 v71, s[2:3]
	s_add_i32 m0, s75, 0x1c00
	v_mfma_f32_16x16x32_bf16 v[212:215], v[172:175], v[168:171], v[212:215]
	global_load_lds_dwordx4 v72, s[2:3]
	s_add_i32 m0, s75, 0x2000
	s_nop 0
	global_load_lds_dwordx4 v73, s[2:3]
	s_waitcnt vmcnt(8)
	ds_read_b128 v[172:175], v89 offset:384
	ds_read_b64_tr_b16 v[140:141], v78 offset:9216
	ds_read_b64_tr_b16 v[142:143], v78 offset:10240
	ds_read_b64_tr_b16 v[144:145], v79 offset:9216
	ds_read_b64_tr_b16 v[146:147], v79 offset:10240
	ds_read_b64_tr_b16 v[148:149], v80 offset:9216
	ds_read_b64_tr_b16 v[150:151], v80 offset:10240
	ds_read_b64_tr_b16 v[152:153], v81 offset:9216
	ds_read_b64_tr_b16 v[154:155], v81 offset:10240
	ds_read_b64_tr_b16 v[156:157], v82 offset:9216
	ds_read_b64_tr_b16 v[158:159], v82 offset:10240
	ds_read_b64_tr_b16 v[160:161], v83 offset:9216
	ds_read_b64_tr_b16 v[162:163], v83 offset:10240
	ds_read_b64_tr_b16 v[164:165], v84 offset:9216
	ds_read_b64_tr_b16 v[166:167], v84 offset:10240
	ds_read_b64_tr_b16 v[168:169], v85 offset:9216
	ds_read_b64_tr_b16 v[170:171], v85 offset:10240
	s_waitcnt lgkmcnt(0)
	v_mfma_f32_16x16x32_bf16 v[184:187], v[172:175], v[140:143], v[184:187]
	v_mfma_f32_16x16x32_bf16 v[188:191], v[172:175], v[144:147], v[188:191]
	v_mfma_f32_16x16x32_bf16 v[192:195], v[172:175], v[148:151], v[192:195]
	v_mfma_f32_16x16x32_bf16 v[196:199], v[172:175], v[152:155], v[196:199]
	v_mfma_f32_16x16x32_bf16 v[200:203], v[172:175], v[156:159], v[200:203]
	v_mfma_f32_16x16x32_bf16 v[204:207], v[172:175], v[160:163], v[204:207]
	v_mfma_f32_16x16x32_bf16 v[208:211], v[172:175], v[164:167], v[208:211]
	v_mfma_f32_16x16x32_bf16 v[212:215], v[172:175], v[168:171], v[212:215]
	s_waitcnt vmcnt(0)
	ds_read_b128 v[172:175], v89 offset:448
	ds_read_b64_tr_b16 v[140:141], v78 offset:1024
	ds_read_b64_tr_b16 v[142:143], v78 offset:2048
	ds_read_b64_tr_b16 v[144:145], v79 offset:1024
	ds_read_b64_tr_b16 v[146:147], v79 offset:2048
	ds_read_b64_tr_b16 v[148:149], v80 offset:1024
	ds_read_b64_tr_b16 v[150:151], v80 offset:2048
	ds_read_b64_tr_b16 v[152:153], v81 offset:1024
	ds_read_b64_tr_b16 v[154:155], v81 offset:2048
	ds_read_b64_tr_b16 v[156:157], v82 offset:1024
	ds_read_b64_tr_b16 v[158:159], v82 offset:2048
	ds_read_b64_tr_b16 v[160:161], v83 offset:1024
	ds_read_b64_tr_b16 v[162:163], v83 offset:2048
	ds_read_b64_tr_b16 v[164:165], v84 offset:1024
	ds_read_b64_tr_b16 v[166:167], v84 offset:2048
	ds_read_b64_tr_b16 v[168:169], v85 offset:1024
	ds_read_b64_tr_b16 v[170:171], v85 offset:2048
	s_waitcnt lgkmcnt(0)
	v_mfma_f32_16x16x32_bf16 v[184:187], v[172:175], v[140:143], v[184:187]
	v_mfma_f32_16x16x32_bf16 v[188:191], v[172:175], v[144:147], v[188:191]
	v_mfma_f32_16x16x32_bf16 v[192:195], v[172:175], v[148:151], v[192:195]
	v_mfma_f32_16x16x32_bf16 v[196:199], v[172:175], v[152:155], v[196:199]
	v_mfma_f32_16x16x32_bf16 v[200:203], v[172:175], v[156:159], v[200:203]
	v_mfma_f32_16x16x32_bf16 v[204:207], v[172:175], v[160:163], v[204:207]
	v_mfma_f32_16x16x32_bf16 v[208:211], v[172:175], v[164:167], v[208:211]
	v_mfma_f32_16x16x32_bf16 v[212:215], v[172:175], v[168:171], v[212:215]
	s_nop 7
	s_mov_b64 exec, 0xffff
	ds_write_b128 v132, v[184:187] offset:0
	ds_write_b128 v132, v[188:191] offset:288
	ds_write_b128 v132, v[192:195] offset:576
	ds_write_b128 v132, v[196:199] offset:864
	ds_write_b128 v132, v[200:203] offset:1152
	ds_write_b128 v132, v[204:207] offset:1440
	ds_write_b128 v132, v[208:211] offset:1728
	ds_write_b128 v132, v[212:215] offset:2016
	s_mov_b64 exec, -1
	s_waitcnt lgkmcnt(0)
	ds_read_b32 v140, v133 offset:0
	ds_read_b32 v141, v133 offset:16
	ds_read_b32 v142, v133 offset:32
	ds_read_b32 v143, v133 offset:48
	ds_read_b32 v144, v133 offset:64
	ds_read_b32 v145, v133 offset:80
	ds_read_b32 v146, v133 offset:96
	ds_read_b32 v147, v133 offset:112
	s_waitcnt lgkmcnt(0)
	v_cvt_pk_bf16_f32 v148, v140, v141
	v_cvt_pk_bf16_f32 v149, v142, v143
	v_cvt_pk_bf16_f32 v150, v144, v145
	v_cvt_pk_bf16_f32 v151, v146, v147
	global_store_dwordx4 v90, v[148:151], s[6:7]
	s_cmp_eq_u32 s74, 0
	s_cbranch_scc0 .Lau_ret1
	v_and_b32_e32 v141, 64, v182
	v_add_u32_e32 v4, 64, v141
	v_xor_b32_e32 v5, 32, v182
	v_cmp_lt_i32_e32 vcc, v5, v4
	s_nop 1
	v_cndmask_b32_e32 v5, v182, v5, vcc
	v_lshlrev_b32_e32 v132, 2, v5
	v_xor_b32_e32 v5, 16, v182
	v_cmp_lt_i32_e32 vcc, v5, v4
	s_nop 1
	v_cndmask_b32_e32 v5, v182, v5, vcc
	v_lshlrev_b32_e32 v133, 2, v5
	v_xor_b32_e32 v5, 8, v182
	v_cmp_lt_i32_e32 vcc, v5, v4
	s_nop 1
	v_cndmask_b32_e32 v5, v182, v5, vcc
	v_lshlrev_b32_e32 v136, 2, v5
	v_xor_b32_e32 v5, 4, v182
	v_cmp_lt_i32_e32 vcc, v5, v4
	s_nop 1
	v_cndmask_b32_e32 v5, v182, v5, vcc
	v_lshlrev_b32_e32 v137, 2, v5
	v_xor_b32_e32 v5, 2, v182
	v_cmp_lt_i32_e32 vcc, v5, v4
	s_nop 1
	v_cndmask_b32_e32 v5, v182, v5, vcc
	v_lshlrev_b32_e32 v139, 2, v5
	v_xor_b32_e32 v5, 1, v182
	v_cmp_lt_i32_e32 vcc, v5, v4
	s_nop 1
	v_cndmask_b32_e32 v5, v182, v5, vcc
	v_lshlrev_b32_e32 v140, 2, v5
	s_branch .Lau_ret0
